# P4 gate epilogue hand-written: gate loads prefetched 7 iterations deep (g0) or all 16 up front (g1) instead of a wait after every load
# speedup vs baseline: 1.0293x; 1.0017x over previous
.LBB0_479:
	s_mov_b32 s74, 0xffff0000
	s_lshl_b32 s68, s6, 8
	s_lshl_b32 s75, s8, 8
	s_cmp_lg_u32 s1, 0
	s_cbranch_scc1 .Lp4e_g1
	v_add_u32_e32 v249, s68, v151
	v_lshlrev_b32_e32 v248, 14, v249
	v_or_b32_e32 v249, s75, v155
	v_lshl_add_u32 v248, v249, 1, v248
	s_add_u32 s32, s38, 0x3000
	s_addc_u32 s33, s39, 0
	global_load_dwordx4 v[134:137], v248, s[32:33]
	s_add_u32 s32, s38, 0x2000
	s_addc_u32 s33, s39, 0
	global_load_dwordx4 v[138:141], v248, s[32:33]
	s_add_u32 s32, s38, 0x3100
	s_addc_u32 s33, s39, 0
	global_load_dwordx4 v[142:145], v248, s[32:33]
	s_add_u32 s32, s38, 0x2100
	s_addc_u32 s33, s39, 0
	global_load_dwordx4 v[146:149], v248, s[32:33]
	s_add_u32 s32, s38, 0x43000
	s_addc_u32 s33, s39, 0
	global_load_dwordx4 v[180:183], v248, s[32:33]
	s_add_u32 s32, s38, 0x42000
	s_addc_u32 s33, s39, 0
	global_load_dwordx4 v[186:189], v248, s[32:33]
	s_add_u32 s32, s38, 0x43100
	s_addc_u32 s33, s39, 0
	global_load_dwordx4 v[212:215], v248, s[32:33]
	s_add_u32 s32, s38, 0x42100
	s_addc_u32 s33, s39, 0
	global_load_dwordx4 v[216:219], v248, s[32:33]
	s_add_u32 s32, s38, 0x83000
	s_addc_u32 s33, s39, 0
	global_load_dwordx4 v[220:223], v248, s[32:33]
	s_add_u32 s32, s38, 0x82000
	s_addc_u32 s33, s39, 0
	global_load_dwordx4 v[224:227], v248, s[32:33]
	s_add_u32 s32, s38, 0x83100
	s_addc_u32 s33, s39, 0
	global_load_dwordx4 v[228:231], v248, s[32:33]
	s_add_u32 s32, s38, 0x82100
	s_addc_u32 s33, s39, 0
	global_load_dwordx4 v[232:235], v248, s[32:33]
	s_add_u32 s32, s38, 0xc3000
	s_addc_u32 s33, s39, 0
	global_load_dwordx4 v[236:239], v248, s[32:33]
	s_add_u32 s32, s38, 0xc2000
	s_addc_u32 s33, s39, 0
	global_load_dwordx4 v[240:243], v248, s[32:33]
	s_waitcnt vmcnt(12)
	v_lshlrev_b32_e32 v3, 16, v134
	v_and_b32_e32 v4, s74, v134
	v_lshlrev_b32_e32 v159, 16, v135
	v_and_b32_e32 v190, s74, v135
	v_lshlrev_b32_e32 v191, 16, v136
	v_and_b32_e32 v203, s74, v136
	v_lshlrev_b32_e32 v204, 16, v137
	v_and_b32_e32 v205, s74, v137
	v_max_f32_e32 v3, v3, v3
	v_max_f32_e32 v4, v4, v4
	v_max_f32_e32 v159, v159, v159
	v_max_f32_e32 v190, v190, v190
	v_max_f32_e32 v191, v191, v191
	v_max_f32_e32 v203, v203, v203
	v_max_f32_e32 v204, v204, v204
	v_max_f32_e32 v205, v205, v205
	v_max_f32_e32 v3, 0xc1f00000, v3
	v_max_f32_e32 v4, 0xc1f00000, v4
	v_max_f32_e32 v159, 0xc1f00000, v159
	v_max_f32_e32 v190, 0xc1f00000, v190
	v_max_f32_e32 v191, 0xc1f00000, v191
	v_max_f32_e32 v203, 0xc1f00000, v203
	v_max_f32_e32 v204, 0xc1f00000, v204
	v_max_f32_e32 v205, 0xc1f00000, v205
	v_mul_f32_e32 v3, 0xbfb8aa3b, v3
	v_mul_f32_e32 v4, 0xbfb8aa3b, v4
	v_mul_f32_e32 v159, 0xbfb8aa3b, v159
	v_mul_f32_e32 v190, 0xbfb8aa3b, v190
	v_mul_f32_e32 v191, 0xbfb8aa3b, v191
	v_mul_f32_e32 v203, 0xbfb8aa3b, v203
	v_mul_f32_e32 v204, 0xbfb8aa3b, v204
	v_mul_f32_e32 v205, 0xbfb8aa3b, v205
	v_exp_f32_e32 v3, v3
	v_exp_f32_e32 v4, v4
	v_exp_f32_e32 v159, v159
	v_exp_f32_e32 v190, v190
	v_exp_f32_e32 v191, v191
	v_exp_f32_e32 v203, v203
	v_exp_f32_e32 v204, v204
	v_exp_f32_e32 v205, v205
	v_add_f32_e32 v3, 1.0, v3
	v_add_f32_e32 v4, 1.0, v4
	v_add_f32_e32 v159, 1.0, v159
	v_add_f32_e32 v190, 1.0, v190
	v_add_f32_e32 v191, 1.0, v191
	v_add_f32_e32 v203, 1.0, v203
	v_add_f32_e32 v204, 1.0, v204
	v_add_f32_e32 v205, 1.0, v205
	v_and_b32_e32 v211, s74, v138
	v_lshlrev_b32_e32 v138, 16, v138
	v_and_b32_e32 v252, s74, v139
	v_lshlrev_b32_e32 v139, 16, v139
	v_and_b32_e32 v253, s74, v140
	v_lshlrev_b32_e32 v140, 16, v140
	v_and_b32_e32 v254, s74, v141
	v_lshlrev_b32_e32 v141, 16, v141
	v_mul_f32_e32 v138, 0xbfb8aa3b, v138
	v_mul_f32_e32 v211, 0xbfb8aa3b, v211
	v_mul_f32_e32 v139, 0xbfb8aa3b, v139
	v_mul_f32_e32 v252, 0xbfb8aa3b, v252
	v_mul_f32_e32 v140, 0xbfb8aa3b, v140
	v_mul_f32_e32 v253, 0xbfb8aa3b, v253
	v_mul_f32_e32 v141, 0xbfb8aa3b, v141
	v_mul_f32_e32 v254, 0xbfb8aa3b, v254
	v_exp_f32_e32 v138, v138
	v_exp_f32_e32 v211, v211
	v_exp_f32_e32 v139, v139
	v_exp_f32_e32 v252, v252
	v_exp_f32_e32 v140, v140
	v_exp_f32_e32 v253, v253
	v_exp_f32_e32 v141, v141
	v_exp_f32_e32 v254, v254
	v_add_f32_e32 v138, 1.0, v138
	v_add_f32_e32 v211, 1.0, v211
	v_add_f32_e32 v139, 1.0, v139
	v_add_f32_e32 v252, 1.0, v252
	v_add_f32_e32 v140, 1.0, v140
	v_add_f32_e32 v253, 1.0, v253
	v_add_f32_e32 v141, 1.0, v141
	v_add_f32_e32 v254, 1.0, v254
	v_rcp_f32_e32 v138, v138
	v_rcp_f32_e32 v211, v211
	v_rcp_f32_e32 v139, v139
	v_rcp_f32_e32 v252, v252
	v_rcp_f32_e32 v140, v140
	v_rcp_f32_e32 v253, v253
	v_rcp_f32_e32 v141, v141
	v_rcp_f32_e32 v254, v254
	v_mul_f32_e32 v134, v3, v138
	v_mul_f32_e32 v135, v4, v211
	v_mul_f32_e32 v136, v159, v139
	v_mul_f32_e32 v137, v190, v252
	v_mul_f32_e32 v138, v191, v140
	v_mul_f32_e32 v139, v203, v253
	v_mul_f32_e32 v140, v204, v141
	v_mul_f32_e32 v141, v205, v254
	v_pk_mul_f32 v[130:131], v[130:131], v[134:135]
	v_pk_mul_f32 v[132:133], v[132:133], v[136:137]
	v_pk_mul_f32 v[126:127], v[126:127], v[138:139]
	v_pk_mul_f32 v[128:129], v[128:129], v[140:141]
	s_add_u32 s32, s38, 0xc3100
	s_addc_u32 s33, s39, 0
	global_load_dwordx4 v[134:137], v248, s[32:33]
	s_add_u32 s32, s38, 0xc2100
	s_addc_u32 s33, s39, 0
	global_load_dwordx4 v[138:141], v248, s[32:33]
	s_waitcnt vmcnt(12)
	v_lshlrev_b32_e32 v3, 16, v142
	v_and_b32_e32 v4, s74, v142
	v_lshlrev_b32_e32 v159, 16, v143
	v_and_b32_e32 v190, s74, v143
	v_lshlrev_b32_e32 v191, 16, v144
	v_and_b32_e32 v203, s74, v144
	v_lshlrev_b32_e32 v204, 16, v145
	v_and_b32_e32 v205, s74, v145
	v_max_f32_e32 v3, v3, v3
	v_max_f32_e32 v4, v4, v4
	v_max_f32_e32 v159, v159, v159
	v_max_f32_e32 v190, v190, v190
	v_max_f32_e32 v191, v191, v191
	v_max_f32_e32 v203, v203, v203
	v_max_f32_e32 v204, v204, v204
	v_max_f32_e32 v205, v205, v205
	v_max_f32_e32 v3, 0xc1f00000, v3
	v_max_f32_e32 v4, 0xc1f00000, v4
	v_max_f32_e32 v159, 0xc1f00000, v159
	v_max_f32_e32 v190, 0xc1f00000, v190
	v_max_f32_e32 v191, 0xc1f00000, v191
	v_max_f32_e32 v203, 0xc1f00000, v203
	v_max_f32_e32 v204, 0xc1f00000, v204
	v_max_f32_e32 v205, 0xc1f00000, v205
	v_mul_f32_e32 v3, 0xbfb8aa3b, v3
	v_mul_f32_e32 v4, 0xbfb8aa3b, v4
	v_mul_f32_e32 v159, 0xbfb8aa3b, v159
	v_mul_f32_e32 v190, 0xbfb8aa3b, v190
	v_mul_f32_e32 v191, 0xbfb8aa3b, v191
	v_mul_f32_e32 v203, 0xbfb8aa3b, v203
	v_mul_f32_e32 v204, 0xbfb8aa3b, v204
	v_mul_f32_e32 v205, 0xbfb8aa3b, v205
	v_exp_f32_e32 v3, v3
	v_exp_f32_e32 v4, v4
	v_exp_f32_e32 v159, v159
	v_exp_f32_e32 v190, v190
	v_exp_f32_e32 v191, v191
	v_exp_f32_e32 v203, v203
	v_exp_f32_e32 v204, v204
	v_exp_f32_e32 v205, v205
	v_add_f32_e32 v3, 1.0, v3
	v_add_f32_e32 v4, 1.0, v4
	v_add_f32_e32 v159, 1.0, v159
	v_add_f32_e32 v190, 1.0, v190
	v_add_f32_e32 v191, 1.0, v191
	v_add_f32_e32 v203, 1.0, v203
	v_add_f32_e32 v204, 1.0, v204
	v_add_f32_e32 v205, 1.0, v205
	v_and_b32_e32 v211, s74, v146
	v_lshlrev_b32_e32 v146, 16, v146
	v_and_b32_e32 v252, s74, v147
	v_lshlrev_b32_e32 v147, 16, v147
	v_and_b32_e32 v253, s74, v148
	v_lshlrev_b32_e32 v148, 16, v148
	v_and_b32_e32 v254, s74, v149
	v_lshlrev_b32_e32 v149, 16, v149
	v_mul_f32_e32 v146, 0xbfb8aa3b, v146
	v_mul_f32_e32 v211, 0xbfb8aa3b, v211
	v_mul_f32_e32 v147, 0xbfb8aa3b, v147
	v_mul_f32_e32 v252, 0xbfb8aa3b, v252
	v_mul_f32_e32 v148, 0xbfb8aa3b, v148
	v_mul_f32_e32 v253, 0xbfb8aa3b, v253
	v_mul_f32_e32 v149, 0xbfb8aa3b, v149
	v_mul_f32_e32 v254, 0xbfb8aa3b, v254
	v_exp_f32_e32 v146, v146
	v_exp_f32_e32 v211, v211
	v_exp_f32_e32 v147, v147
	v_exp_f32_e32 v252, v252
	v_exp_f32_e32 v148, v148
	v_exp_f32_e32 v253, v253
	v_exp_f32_e32 v149, v149
	v_exp_f32_e32 v254, v254
	v_add_f32_e32 v146, 1.0, v146
	v_add_f32_e32 v211, 1.0, v211
	v_add_f32_e32 v147, 1.0, v147
	v_add_f32_e32 v252, 1.0, v252
	v_add_f32_e32 v148, 1.0, v148
	v_add_f32_e32 v253, 1.0, v253
	v_add_f32_e32 v149, 1.0, v149
	v_add_f32_e32 v254, 1.0, v254
	v_rcp_f32_e32 v146, v146
	v_rcp_f32_e32 v211, v211
	v_rcp_f32_e32 v147, v147
	v_rcp_f32_e32 v252, v252
	v_rcp_f32_e32 v148, v148
	v_rcp_f32_e32 v253, v253
	v_rcp_f32_e32 v149, v149
	v_rcp_f32_e32 v254, v254
	v_mul_f32_e32 v142, v3, v146
	v_mul_f32_e32 v143, v4, v211
	v_mul_f32_e32 v144, v159, v147
	v_mul_f32_e32 v145, v190, v252
	v_mul_f32_e32 v146, v191, v148
	v_mul_f32_e32 v147, v203, v253
	v_mul_f32_e32 v148, v204, v149
	v_mul_f32_e32 v149, v205, v254
	v_pk_mul_f32 v[98:99], v[98:99], v[142:143]
	v_pk_mul_f32 v[100:101], v[100:101], v[144:145]
	v_pk_mul_f32 v[94:95], v[94:95], v[146:147]
	v_pk_mul_f32 v[96:97], v[96:97], v[148:149]
	s_add_u32 s32, s38, 0x203000
	s_addc_u32 s33, s39, 0
	global_load_dwordx4 v[142:145], v248, s[32:33]
	s_add_u32 s32, s38, 0x202000
	s_addc_u32 s33, s39, 0
	global_load_dwordx4 v[146:149], v248, s[32:33]
	s_waitcnt vmcnt(12)
	v_lshlrev_b32_e32 v3, 16, v180
	v_and_b32_e32 v4, s74, v180
	v_lshlrev_b32_e32 v159, 16, v181
	v_and_b32_e32 v190, s74, v181
	v_lshlrev_b32_e32 v191, 16, v182
	v_and_b32_e32 v203, s74, v182
	v_lshlrev_b32_e32 v204, 16, v183
	v_and_b32_e32 v205, s74, v183
	v_max_f32_e32 v3, v3, v3
	v_max_f32_e32 v4, v4, v4
	v_max_f32_e32 v159, v159, v159
	v_max_f32_e32 v190, v190, v190
	v_max_f32_e32 v191, v191, v191
	v_max_f32_e32 v203, v203, v203
	v_max_f32_e32 v204, v204, v204
	v_max_f32_e32 v205, v205, v205
	v_max_f32_e32 v3, 0xc1f00000, v3
	v_max_f32_e32 v4, 0xc1f00000, v4
	v_max_f32_e32 v159, 0xc1f00000, v159
	v_max_f32_e32 v190, 0xc1f00000, v190
	v_max_f32_e32 v191, 0xc1f00000, v191
	v_max_f32_e32 v203, 0xc1f00000, v203
	v_max_f32_e32 v204, 0xc1f00000, v204
	v_max_f32_e32 v205, 0xc1f00000, v205
	v_mul_f32_e32 v3, 0xbfb8aa3b, v3
	v_mul_f32_e32 v4, 0xbfb8aa3b, v4
	v_mul_f32_e32 v159, 0xbfb8aa3b, v159
	v_mul_f32_e32 v190, 0xbfb8aa3b, v190
	v_mul_f32_e32 v191, 0xbfb8aa3b, v191
	v_mul_f32_e32 v203, 0xbfb8aa3b, v203
	v_mul_f32_e32 v204, 0xbfb8aa3b, v204
	v_mul_f32_e32 v205, 0xbfb8aa3b, v205
	v_exp_f32_e32 v3, v3
	v_exp_f32_e32 v4, v4
	v_exp_f32_e32 v159, v159
	v_exp_f32_e32 v190, v190
	v_exp_f32_e32 v191, v191
	v_exp_f32_e32 v203, v203
	v_exp_f32_e32 v204, v204
	v_exp_f32_e32 v205, v205
	v_add_f32_e32 v3, 1.0, v3
	v_add_f32_e32 v4, 1.0, v4
	v_add_f32_e32 v159, 1.0, v159
	v_add_f32_e32 v190, 1.0, v190
	v_add_f32_e32 v191, 1.0, v191
	v_add_f32_e32 v203, 1.0, v203
	v_add_f32_e32 v204, 1.0, v204
	v_add_f32_e32 v205, 1.0, v205
	v_and_b32_e32 v211, s74, v186
	v_lshlrev_b32_e32 v186, 16, v186
	v_and_b32_e32 v252, s74, v187
	v_lshlrev_b32_e32 v187, 16, v187
	v_and_b32_e32 v253, s74, v188
	v_lshlrev_b32_e32 v188, 16, v188
	v_and_b32_e32 v254, s74, v189
	v_lshlrev_b32_e32 v189, 16, v189
	v_mul_f32_e32 v186, 0xbfb8aa3b, v186
	v_mul_f32_e32 v211, 0xbfb8aa3b, v211
	v_mul_f32_e32 v187, 0xbfb8aa3b, v187
	v_mul_f32_e32 v252, 0xbfb8aa3b, v252
	v_mul_f32_e32 v188, 0xbfb8aa3b, v188
	v_mul_f32_e32 v253, 0xbfb8aa3b, v253
	v_mul_f32_e32 v189, 0xbfb8aa3b, v189
	v_mul_f32_e32 v254, 0xbfb8aa3b, v254
	v_exp_f32_e32 v186, v186
	v_exp_f32_e32 v211, v211
	v_exp_f32_e32 v187, v187
	v_exp_f32_e32 v252, v252
	v_exp_f32_e32 v188, v188
	v_exp_f32_e32 v253, v253
	v_exp_f32_e32 v189, v189
	v_exp_f32_e32 v254, v254
	v_add_f32_e32 v186, 1.0, v186
	v_add_f32_e32 v211, 1.0, v211
	v_add_f32_e32 v187, 1.0, v187
	v_add_f32_e32 v252, 1.0, v252
	v_add_f32_e32 v188, 1.0, v188
	v_add_f32_e32 v253, 1.0, v253
	v_add_f32_e32 v189, 1.0, v189
	v_add_f32_e32 v254, 1.0, v254
	v_rcp_f32_e32 v186, v186
	v_rcp_f32_e32 v211, v211
	v_rcp_f32_e32 v187, v187
	v_rcp_f32_e32 v252, v252
	v_rcp_f32_e32 v188, v188
	v_rcp_f32_e32 v253, v253
	v_rcp_f32_e32 v189, v189
	v_rcp_f32_e32 v254, v254
	v_mul_f32_e32 v180, v3, v186
	v_mul_f32_e32 v181, v4, v211
	v_mul_f32_e32 v182, v159, v187
	v_mul_f32_e32 v183, v190, v252
	v_mul_f32_e32 v186, v191, v188
	v_mul_f32_e32 v187, v203, v253
	v_mul_f32_e32 v188, v204, v189
	v_mul_f32_e32 v189, v205, v254
	v_pk_mul_f32 v[122:123], v[122:123], v[180:181]
	v_pk_mul_f32 v[124:125], v[124:125], v[182:183]
	v_pk_mul_f32 v[118:119], v[118:119], v[186:187]
	v_pk_mul_f32 v[120:121], v[120:121], v[188:189]
	s_add_u32 s32, s38, 0x203100
	s_addc_u32 s33, s39, 0
	global_load_dwordx4 v[180:183], v248, s[32:33]
	s_add_u32 s32, s38, 0x202100
	s_addc_u32 s33, s39, 0
	global_load_dwordx4 v[186:189], v248, s[32:33]
	s_waitcnt vmcnt(12)
	v_lshlrev_b32_e32 v3, 16, v212
	v_and_b32_e32 v4, s74, v212
	v_lshlrev_b32_e32 v159, 16, v213
	v_and_b32_e32 v190, s74, v213
	v_lshlrev_b32_e32 v191, 16, v214
	v_and_b32_e32 v203, s74, v214
	v_lshlrev_b32_e32 v204, 16, v215
	v_and_b32_e32 v205, s74, v215
	v_max_f32_e32 v3, v3, v3
	v_max_f32_e32 v4, v4, v4
	v_max_f32_e32 v159, v159, v159
	v_max_f32_e32 v190, v190, v190
	v_max_f32_e32 v191, v191, v191
	v_max_f32_e32 v203, v203, v203
	v_max_f32_e32 v204, v204, v204
	v_max_f32_e32 v205, v205, v205
	v_max_f32_e32 v3, 0xc1f00000, v3
	v_max_f32_e32 v4, 0xc1f00000, v4
	v_max_f32_e32 v159, 0xc1f00000, v159
	v_max_f32_e32 v190, 0xc1f00000, v190
	v_max_f32_e32 v191, 0xc1f00000, v191
	v_max_f32_e32 v203, 0xc1f00000, v203
	v_max_f32_e32 v204, 0xc1f00000, v204
	v_max_f32_e32 v205, 0xc1f00000, v205
	v_mul_f32_e32 v3, 0xbfb8aa3b, v3
	v_mul_f32_e32 v4, 0xbfb8aa3b, v4
	v_mul_f32_e32 v159, 0xbfb8aa3b, v159
	v_mul_f32_e32 v190, 0xbfb8aa3b, v190
	v_mul_f32_e32 v191, 0xbfb8aa3b, v191
	v_mul_f32_e32 v203, 0xbfb8aa3b, v203
	v_mul_f32_e32 v204, 0xbfb8aa3b, v204
	v_mul_f32_e32 v205, 0xbfb8aa3b, v205
	v_exp_f32_e32 v3, v3
	v_exp_f32_e32 v4, v4
	v_exp_f32_e32 v159, v159
	v_exp_f32_e32 v190, v190
	v_exp_f32_e32 v191, v191
	v_exp_f32_e32 v203, v203
	v_exp_f32_e32 v204, v204
	v_exp_f32_e32 v205, v205
	v_add_f32_e32 v3, 1.0, v3
	v_add_f32_e32 v4, 1.0, v4
	v_add_f32_e32 v159, 1.0, v159
	v_add_f32_e32 v190, 1.0, v190
	v_add_f32_e32 v191, 1.0, v191
	v_add_f32_e32 v203, 1.0, v203
	v_add_f32_e32 v204, 1.0, v204
	v_add_f32_e32 v205, 1.0, v205
	v_and_b32_e32 v211, s74, v216
	v_lshlrev_b32_e32 v216, 16, v216
	v_and_b32_e32 v252, s74, v217
	v_lshlrev_b32_e32 v217, 16, v217
	v_and_b32_e32 v253, s74, v218
	v_lshlrev_b32_e32 v218, 16, v218
	v_and_b32_e32 v254, s74, v219
	v_lshlrev_b32_e32 v219, 16, v219
	v_mul_f32_e32 v216, 0xbfb8aa3b, v216
	v_mul_f32_e32 v211, 0xbfb8aa3b, v211
	v_mul_f32_e32 v217, 0xbfb8aa3b, v217
	v_mul_f32_e32 v252, 0xbfb8aa3b, v252
	v_mul_f32_e32 v218, 0xbfb8aa3b, v218
	v_mul_f32_e32 v253, 0xbfb8aa3b, v253
	v_mul_f32_e32 v219, 0xbfb8aa3b, v219
	v_mul_f32_e32 v254, 0xbfb8aa3b, v254
	v_exp_f32_e32 v216, v216
	v_exp_f32_e32 v211, v211
	v_exp_f32_e32 v217, v217
	v_exp_f32_e32 v252, v252
	v_exp_f32_e32 v218, v218
	v_exp_f32_e32 v253, v253
	v_exp_f32_e32 v219, v219
	v_exp_f32_e32 v254, v254
	v_add_f32_e32 v216, 1.0, v216
	v_add_f32_e32 v211, 1.0, v211
	v_add_f32_e32 v217, 1.0, v217
	v_add_f32_e32 v252, 1.0, v252
	v_add_f32_e32 v218, 1.0, v218
	v_add_f32_e32 v253, 1.0, v253
	v_add_f32_e32 v219, 1.0, v219
	v_add_f32_e32 v254, 1.0, v254
	v_rcp_f32_e32 v216, v216
	v_rcp_f32_e32 v211, v211
	v_rcp_f32_e32 v217, v217
	v_rcp_f32_e32 v252, v252
	v_rcp_f32_e32 v218, v218
	v_rcp_f32_e32 v253, v253
	v_rcp_f32_e32 v219, v219
	v_rcp_f32_e32 v254, v254
	v_mul_f32_e32 v212, v3, v216
	v_mul_f32_e32 v213, v4, v211
	v_mul_f32_e32 v214, v159, v217
	v_mul_f32_e32 v215, v190, v252
	v_mul_f32_e32 v216, v191, v218
	v_mul_f32_e32 v217, v203, v253
	v_mul_f32_e32 v218, v204, v219
	v_mul_f32_e32 v219, v205, v254
	v_pk_mul_f32 v[90:91], v[90:91], v[212:213]
	v_pk_mul_f32 v[92:93], v[92:93], v[214:215]
	v_pk_mul_f32 v[86:87], v[86:87], v[216:217]
	v_pk_mul_f32 v[88:89], v[88:89], v[218:219]
	s_add_u32 s32, s38, 0x243000
	s_addc_u32 s33, s39, 0
	global_load_dwordx4 v[212:215], v248, s[32:33]
	s_add_u32 s32, s38, 0x242000
	s_addc_u32 s33, s39, 0
	global_load_dwordx4 v[216:219], v248, s[32:33]
	s_waitcnt vmcnt(12)
	v_lshlrev_b32_e32 v3, 16, v220
	v_and_b32_e32 v4, s74, v220
	v_lshlrev_b32_e32 v159, 16, v221
	v_and_b32_e32 v190, s74, v221
	v_lshlrev_b32_e32 v191, 16, v222
	v_and_b32_e32 v203, s74, v222
	v_lshlrev_b32_e32 v204, 16, v223
	v_and_b32_e32 v205, s74, v223
	v_max_f32_e32 v3, v3, v3
	v_max_f32_e32 v4, v4, v4
	v_max_f32_e32 v159, v159, v159
	v_max_f32_e32 v190, v190, v190
	v_max_f32_e32 v191, v191, v191
	v_max_f32_e32 v203, v203, v203
	v_max_f32_e32 v204, v204, v204
	v_max_f32_e32 v205, v205, v205
	v_max_f32_e32 v3, 0xc1f00000, v3
	v_max_f32_e32 v4, 0xc1f00000, v4
	v_max_f32_e32 v159, 0xc1f00000, v159
	v_max_f32_e32 v190, 0xc1f00000, v190
	v_max_f32_e32 v191, 0xc1f00000, v191
	v_max_f32_e32 v203, 0xc1f00000, v203
	v_max_f32_e32 v204, 0xc1f00000, v204
	v_max_f32_e32 v205, 0xc1f00000, v205
	v_mul_f32_e32 v3, 0xbfb8aa3b, v3
	v_mul_f32_e32 v4, 0xbfb8aa3b, v4
	v_mul_f32_e32 v159, 0xbfb8aa3b, v159
	v_mul_f32_e32 v190, 0xbfb8aa3b, v190
	v_mul_f32_e32 v191, 0xbfb8aa3b, v191
	v_mul_f32_e32 v203, 0xbfb8aa3b, v203
	v_mul_f32_e32 v204, 0xbfb8aa3b, v204
	v_mul_f32_e32 v205, 0xbfb8aa3b, v205
	v_exp_f32_e32 v3, v3
	v_exp_f32_e32 v4, v4
	v_exp_f32_e32 v159, v159
	v_exp_f32_e32 v190, v190
	v_exp_f32_e32 v191, v191
	v_exp_f32_e32 v203, v203
	v_exp_f32_e32 v204, v204
	v_exp_f32_e32 v205, v205
	v_add_f32_e32 v3, 1.0, v3
	v_add_f32_e32 v4, 1.0, v4
	v_add_f32_e32 v159, 1.0, v159
	v_add_f32_e32 v190, 1.0, v190
	v_add_f32_e32 v191, 1.0, v191
	v_add_f32_e32 v203, 1.0, v203
	v_add_f32_e32 v204, 1.0, v204
	v_add_f32_e32 v205, 1.0, v205
	v_and_b32_e32 v211, s74, v224
	v_lshlrev_b32_e32 v224, 16, v224
	v_and_b32_e32 v252, s74, v225
	v_lshlrev_b32_e32 v225, 16, v225
	v_and_b32_e32 v253, s74, v226
	v_lshlrev_b32_e32 v226, 16, v226
	v_and_b32_e32 v254, s74, v227
	v_lshlrev_b32_e32 v227, 16, v227
	v_mul_f32_e32 v224, 0xbfb8aa3b, v224
	v_mul_f32_e32 v211, 0xbfb8aa3b, v211
	v_mul_f32_e32 v225, 0xbfb8aa3b, v225
	v_mul_f32_e32 v252, 0xbfb8aa3b, v252
	v_mul_f32_e32 v226, 0xbfb8aa3b, v226
	v_mul_f32_e32 v253, 0xbfb8aa3b, v253
	v_mul_f32_e32 v227, 0xbfb8aa3b, v227
	v_mul_f32_e32 v254, 0xbfb8aa3b, v254
	v_exp_f32_e32 v224, v224
	v_exp_f32_e32 v211, v211
	v_exp_f32_e32 v225, v225
	v_exp_f32_e32 v252, v252
	v_exp_f32_e32 v226, v226
	v_exp_f32_e32 v253, v253
	v_exp_f32_e32 v227, v227
	v_exp_f32_e32 v254, v254
	v_add_f32_e32 v224, 1.0, v224
	v_add_f32_e32 v211, 1.0, v211
	v_add_f32_e32 v225, 1.0, v225
	v_add_f32_e32 v252, 1.0, v252
	v_add_f32_e32 v226, 1.0, v226
	v_add_f32_e32 v253, 1.0, v253
	v_add_f32_e32 v227, 1.0, v227
	v_add_f32_e32 v254, 1.0, v254
	v_rcp_f32_e32 v224, v224
	v_rcp_f32_e32 v211, v211
	v_rcp_f32_e32 v225, v225
	v_rcp_f32_e32 v252, v252
	v_rcp_f32_e32 v226, v226
	v_rcp_f32_e32 v253, v253
	v_rcp_f32_e32 v227, v227
	v_rcp_f32_e32 v254, v254
	v_mul_f32_e32 v220, v3, v224
	v_mul_f32_e32 v221, v4, v211
	v_mul_f32_e32 v222, v159, v225
	v_mul_f32_e32 v223, v190, v252
	v_mul_f32_e32 v224, v191, v226
	v_mul_f32_e32 v225, v203, v253
	v_mul_f32_e32 v226, v204, v227
	v_mul_f32_e32 v227, v205, v254
	v_pk_mul_f32 v[114:115], v[114:115], v[220:221]
	v_pk_mul_f32 v[116:117], v[116:117], v[222:223]
	v_pk_mul_f32 v[110:111], v[110:111], v[224:225]
	v_pk_mul_f32 v[112:113], v[112:113], v[226:227]
	s_add_u32 s32, s38, 0x243100
	s_addc_u32 s33, s39, 0
	global_load_dwordx4 v[220:223], v248, s[32:33]
	s_add_u32 s32, s38, 0x242100
	s_addc_u32 s33, s39, 0
	global_load_dwordx4 v[224:227], v248, s[32:33]
	s_waitcnt vmcnt(12)
	v_lshlrev_b32_e32 v3, 16, v228
	v_and_b32_e32 v4, s74, v228
	v_lshlrev_b32_e32 v159, 16, v229
	v_and_b32_e32 v190, s74, v229
	v_lshlrev_b32_e32 v191, 16, v230
	v_and_b32_e32 v203, s74, v230
	v_lshlrev_b32_e32 v204, 16, v231
	v_and_b32_e32 v205, s74, v231
	v_max_f32_e32 v3, v3, v3
	v_max_f32_e32 v4, v4, v4
	v_max_f32_e32 v159, v159, v159
	v_max_f32_e32 v190, v190, v190
	v_max_f32_e32 v191, v191, v191
	v_max_f32_e32 v203, v203, v203
	v_max_f32_e32 v204, v204, v204
	v_max_f32_e32 v205, v205, v205
	v_max_f32_e32 v3, 0xc1f00000, v3
	v_max_f32_e32 v4, 0xc1f00000, v4
	v_max_f32_e32 v159, 0xc1f00000, v159
	v_max_f32_e32 v190, 0xc1f00000, v190
	v_max_f32_e32 v191, 0xc1f00000, v191
	v_max_f32_e32 v203, 0xc1f00000, v203
	v_max_f32_e32 v204, 0xc1f00000, v204
	v_max_f32_e32 v205, 0xc1f00000, v205
	v_mul_f32_e32 v3, 0xbfb8aa3b, v3
	v_mul_f32_e32 v4, 0xbfb8aa3b, v4
	v_mul_f32_e32 v159, 0xbfb8aa3b, v159
	v_mul_f32_e32 v190, 0xbfb8aa3b, v190
	v_mul_f32_e32 v191, 0xbfb8aa3b, v191
	v_mul_f32_e32 v203, 0xbfb8aa3b, v203
	v_mul_f32_e32 v204, 0xbfb8aa3b, v204
	v_mul_f32_e32 v205, 0xbfb8aa3b, v205
	v_exp_f32_e32 v3, v3
	v_exp_f32_e32 v4, v4
	v_exp_f32_e32 v159, v159
	v_exp_f32_e32 v190, v190
	v_exp_f32_e32 v191, v191
	v_exp_f32_e32 v203, v203
	v_exp_f32_e32 v204, v204
	v_exp_f32_e32 v205, v205
	v_add_f32_e32 v3, 1.0, v3
	v_add_f32_e32 v4, 1.0, v4
	v_add_f32_e32 v159, 1.0, v159
	v_add_f32_e32 v190, 1.0, v190
	v_add_f32_e32 v191, 1.0, v191
	v_add_f32_e32 v203, 1.0, v203
	v_add_f32_e32 v204, 1.0, v204
	v_add_f32_e32 v205, 1.0, v205
	v_and_b32_e32 v211, s74, v232
	v_lshlrev_b32_e32 v232, 16, v232
	v_and_b32_e32 v252, s74, v233
	v_lshlrev_b32_e32 v233, 16, v233
	v_and_b32_e32 v253, s74, v234
	v_lshlrev_b32_e32 v234, 16, v234
	v_and_b32_e32 v254, s74, v235
	v_lshlrev_b32_e32 v235, 16, v235
	v_mul_f32_e32 v232, 0xbfb8aa3b, v232
	v_mul_f32_e32 v211, 0xbfb8aa3b, v211
	v_mul_f32_e32 v233, 0xbfb8aa3b, v233
	v_mul_f32_e32 v252, 0xbfb8aa3b, v252
	v_mul_f32_e32 v234, 0xbfb8aa3b, v234
	v_mul_f32_e32 v253, 0xbfb8aa3b, v253
	v_mul_f32_e32 v235, 0xbfb8aa3b, v235
	v_mul_f32_e32 v254, 0xbfb8aa3b, v254
	v_exp_f32_e32 v232, v232
	v_exp_f32_e32 v211, v211
	v_exp_f32_e32 v233, v233
	v_exp_f32_e32 v252, v252
	v_exp_f32_e32 v234, v234
	v_exp_f32_e32 v253, v253
	v_exp_f32_e32 v235, v235
	v_exp_f32_e32 v254, v254
	v_add_f32_e32 v232, 1.0, v232
	v_add_f32_e32 v211, 1.0, v211
	v_add_f32_e32 v233, 1.0, v233
	v_add_f32_e32 v252, 1.0, v252
	v_add_f32_e32 v234, 1.0, v234
	v_add_f32_e32 v253, 1.0, v253
	v_add_f32_e32 v235, 1.0, v235
	v_add_f32_e32 v254, 1.0, v254
	v_rcp_f32_e32 v232, v232
	v_rcp_f32_e32 v211, v211
	v_rcp_f32_e32 v233, v233
	v_rcp_f32_e32 v252, v252
	v_rcp_f32_e32 v234, v234
	v_rcp_f32_e32 v253, v253
	v_rcp_f32_e32 v235, v235
	v_rcp_f32_e32 v254, v254
	v_mul_f32_e32 v228, v3, v232
	v_mul_f32_e32 v229, v4, v211
	v_mul_f32_e32 v230, v159, v233
	v_mul_f32_e32 v231, v190, v252
	v_mul_f32_e32 v232, v191, v234
	v_mul_f32_e32 v233, v203, v253
	v_mul_f32_e32 v234, v204, v235
	v_mul_f32_e32 v235, v205, v254
	v_pk_mul_f32 v[82:83], v[82:83], v[228:229]
	v_pk_mul_f32 v[84:85], v[84:85], v[230:231]
	v_pk_mul_f32 v[78:79], v[78:79], v[232:233]
	v_pk_mul_f32 v[80:81], v[80:81], v[234:235]
	s_add_u32 s32, s38, 0x283000
	s_addc_u32 s33, s39, 0
	global_load_dwordx4 v[228:231], v248, s[32:33]
	s_add_u32 s32, s38, 0x282000
	s_addc_u32 s33, s39, 0
	global_load_dwordx4 v[232:235], v248, s[32:33]
	s_waitcnt vmcnt(12)
	v_lshlrev_b32_e32 v3, 16, v236
	v_and_b32_e32 v4, s74, v236
	v_lshlrev_b32_e32 v159, 16, v237
	v_and_b32_e32 v190, s74, v237
	v_lshlrev_b32_e32 v191, 16, v238
	v_and_b32_e32 v203, s74, v238
	v_lshlrev_b32_e32 v204, 16, v239
	v_and_b32_e32 v205, s74, v239
	v_max_f32_e32 v3, v3, v3
	v_max_f32_e32 v4, v4, v4
	v_max_f32_e32 v159, v159, v159
	v_max_f32_e32 v190, v190, v190
	v_max_f32_e32 v191, v191, v191
	v_max_f32_e32 v203, v203, v203
	v_max_f32_e32 v204, v204, v204
	v_max_f32_e32 v205, v205, v205
	v_max_f32_e32 v3, 0xc1f00000, v3
	v_max_f32_e32 v4, 0xc1f00000, v4
	v_max_f32_e32 v159, 0xc1f00000, v159
	v_max_f32_e32 v190, 0xc1f00000, v190
	v_max_f32_e32 v191, 0xc1f00000, v191
	v_max_f32_e32 v203, 0xc1f00000, v203
	v_max_f32_e32 v204, 0xc1f00000, v204
	v_max_f32_e32 v205, 0xc1f00000, v205
	v_mul_f32_e32 v3, 0xbfb8aa3b, v3
	v_mul_f32_e32 v4, 0xbfb8aa3b, v4
	v_mul_f32_e32 v159, 0xbfb8aa3b, v159
	v_mul_f32_e32 v190, 0xbfb8aa3b, v190
	v_mul_f32_e32 v191, 0xbfb8aa3b, v191
	v_mul_f32_e32 v203, 0xbfb8aa3b, v203
	v_mul_f32_e32 v204, 0xbfb8aa3b, v204
	v_mul_f32_e32 v205, 0xbfb8aa3b, v205
	v_exp_f32_e32 v3, v3
	v_exp_f32_e32 v4, v4
	v_exp_f32_e32 v159, v159
	v_exp_f32_e32 v190, v190
	v_exp_f32_e32 v191, v191
	v_exp_f32_e32 v203, v203
	v_exp_f32_e32 v204, v204
	v_exp_f32_e32 v205, v205
	v_add_f32_e32 v3, 1.0, v3
	v_add_f32_e32 v4, 1.0, v4
	v_add_f32_e32 v159, 1.0, v159
	v_add_f32_e32 v190, 1.0, v190
	v_add_f32_e32 v191, 1.0, v191
	v_add_f32_e32 v203, 1.0, v203
	v_add_f32_e32 v204, 1.0, v204
	v_add_f32_e32 v205, 1.0, v205
	v_and_b32_e32 v211, s74, v240
	v_lshlrev_b32_e32 v240, 16, v240
	v_and_b32_e32 v252, s74, v241
	v_lshlrev_b32_e32 v241, 16, v241
	v_and_b32_e32 v253, s74, v242
	v_lshlrev_b32_e32 v242, 16, v242
	v_and_b32_e32 v254, s74, v243
	v_lshlrev_b32_e32 v243, 16, v243
	v_mul_f32_e32 v240, 0xbfb8aa3b, v240
	v_mul_f32_e32 v211, 0xbfb8aa3b, v211
	v_mul_f32_e32 v241, 0xbfb8aa3b, v241
	v_mul_f32_e32 v252, 0xbfb8aa3b, v252
	v_mul_f32_e32 v242, 0xbfb8aa3b, v242
	v_mul_f32_e32 v253, 0xbfb8aa3b, v253
	v_mul_f32_e32 v243, 0xbfb8aa3b, v243
	v_mul_f32_e32 v254, 0xbfb8aa3b, v254
	v_exp_f32_e32 v240, v240
	v_exp_f32_e32 v211, v211
	v_exp_f32_e32 v241, v241
	v_exp_f32_e32 v252, v252
	v_exp_f32_e32 v242, v242
	v_exp_f32_e32 v253, v253
	v_exp_f32_e32 v243, v243
	v_exp_f32_e32 v254, v254
	v_add_f32_e32 v240, 1.0, v240
	v_add_f32_e32 v211, 1.0, v211
	v_add_f32_e32 v241, 1.0, v241
	v_add_f32_e32 v252, 1.0, v252
	v_add_f32_e32 v242, 1.0, v242
	v_add_f32_e32 v253, 1.0, v253
	v_add_f32_e32 v243, 1.0, v243
	v_add_f32_e32 v254, 1.0, v254
	v_rcp_f32_e32 v240, v240
	v_rcp_f32_e32 v211, v211
	v_rcp_f32_e32 v241, v241
	v_rcp_f32_e32 v252, v252
	v_rcp_f32_e32 v242, v242
	v_rcp_f32_e32 v253, v253
	v_rcp_f32_e32 v243, v243
	v_rcp_f32_e32 v254, v254
	v_mul_f32_e32 v236, v3, v240
	v_mul_f32_e32 v237, v4, v211
	v_mul_f32_e32 v238, v159, v241
	v_mul_f32_e32 v239, v190, v252
	v_mul_f32_e32 v240, v191, v242
	v_mul_f32_e32 v241, v203, v253
	v_mul_f32_e32 v242, v204, v243
	v_mul_f32_e32 v243, v205, v254
	v_pk_mul_f32 v[106:107], v[106:107], v[236:237]
	v_pk_mul_f32 v[108:109], v[108:109], v[238:239]
	v_pk_mul_f32 v[102:103], v[102:103], v[240:241]
	v_pk_mul_f32 v[104:105], v[104:105], v[242:243]
	s_add_u32 s32, s38, 0x283100
	s_addc_u32 s33, s39, 0
	global_load_dwordx4 v[236:239], v248, s[32:33]
	s_add_u32 s32, s38, 0x282100
	s_addc_u32 s33, s39, 0
	global_load_dwordx4 v[240:243], v248, s[32:33]
	s_waitcnt vmcnt(12)
	v_lshlrev_b32_e32 v3, 16, v134
	v_and_b32_e32 v4, s74, v134
	v_lshlrev_b32_e32 v159, 16, v135
	v_and_b32_e32 v190, s74, v135
	v_lshlrev_b32_e32 v191, 16, v136
	v_and_b32_e32 v203, s74, v136
	v_lshlrev_b32_e32 v204, 16, v137
	v_and_b32_e32 v205, s74, v137
	v_max_f32_e32 v3, v3, v3
	v_max_f32_e32 v4, v4, v4
	v_max_f32_e32 v159, v159, v159
	v_max_f32_e32 v190, v190, v190
	v_max_f32_e32 v191, v191, v191
	v_max_f32_e32 v203, v203, v203
	v_max_f32_e32 v204, v204, v204
	v_max_f32_e32 v205, v205, v205
	v_max_f32_e32 v3, 0xc1f00000, v3
	v_max_f32_e32 v4, 0xc1f00000, v4
	v_max_f32_e32 v159, 0xc1f00000, v159
	v_max_f32_e32 v190, 0xc1f00000, v190
	v_max_f32_e32 v191, 0xc1f00000, v191
	v_max_f32_e32 v203, 0xc1f00000, v203
	v_max_f32_e32 v204, 0xc1f00000, v204
	v_max_f32_e32 v205, 0xc1f00000, v205
	v_mul_f32_e32 v3, 0xbfb8aa3b, v3
	v_mul_f32_e32 v4, 0xbfb8aa3b, v4
	v_mul_f32_e32 v159, 0xbfb8aa3b, v159
	v_mul_f32_e32 v190, 0xbfb8aa3b, v190
	v_mul_f32_e32 v191, 0xbfb8aa3b, v191
	v_mul_f32_e32 v203, 0xbfb8aa3b, v203
	v_mul_f32_e32 v204, 0xbfb8aa3b, v204
	v_mul_f32_e32 v205, 0xbfb8aa3b, v205
	v_exp_f32_e32 v3, v3
	v_exp_f32_e32 v4, v4
	v_exp_f32_e32 v159, v159
	v_exp_f32_e32 v190, v190
	v_exp_f32_e32 v191, v191
	v_exp_f32_e32 v203, v203
	v_exp_f32_e32 v204, v204
	v_exp_f32_e32 v205, v205
	v_add_f32_e32 v3, 1.0, v3
	v_add_f32_e32 v4, 1.0, v4
	v_add_f32_e32 v159, 1.0, v159
	v_add_f32_e32 v190, 1.0, v190
	v_add_f32_e32 v191, 1.0, v191
	v_add_f32_e32 v203, 1.0, v203
	v_add_f32_e32 v204, 1.0, v204
	v_add_f32_e32 v205, 1.0, v205
	v_and_b32_e32 v211, s74, v138
	v_lshlrev_b32_e32 v138, 16, v138
	v_and_b32_e32 v252, s74, v139
	v_lshlrev_b32_e32 v139, 16, v139
	v_and_b32_e32 v253, s74, v140
	v_lshlrev_b32_e32 v140, 16, v140
	v_and_b32_e32 v254, s74, v141
	v_lshlrev_b32_e32 v141, 16, v141
	v_mul_f32_e32 v138, 0xbfb8aa3b, v138
	v_mul_f32_e32 v211, 0xbfb8aa3b, v211
	v_mul_f32_e32 v139, 0xbfb8aa3b, v139
	v_mul_f32_e32 v252, 0xbfb8aa3b, v252
	v_mul_f32_e32 v140, 0xbfb8aa3b, v140
	v_mul_f32_e32 v253, 0xbfb8aa3b, v253
	v_mul_f32_e32 v141, 0xbfb8aa3b, v141
	v_mul_f32_e32 v254, 0xbfb8aa3b, v254
	v_exp_f32_e32 v138, v138
	v_exp_f32_e32 v211, v211
	v_exp_f32_e32 v139, v139
	v_exp_f32_e32 v252, v252
	v_exp_f32_e32 v140, v140
	v_exp_f32_e32 v253, v253
	v_exp_f32_e32 v141, v141
	v_exp_f32_e32 v254, v254
	v_add_f32_e32 v138, 1.0, v138
	v_add_f32_e32 v211, 1.0, v211
	v_add_f32_e32 v139, 1.0, v139
	v_add_f32_e32 v252, 1.0, v252
	v_add_f32_e32 v140, 1.0, v140
	v_add_f32_e32 v253, 1.0, v253
	v_add_f32_e32 v141, 1.0, v141
	v_add_f32_e32 v254, 1.0, v254
	v_rcp_f32_e32 v138, v138
	v_rcp_f32_e32 v211, v211
	v_rcp_f32_e32 v139, v139
	v_rcp_f32_e32 v252, v252
	v_rcp_f32_e32 v140, v140
	v_rcp_f32_e32 v253, v253
	v_rcp_f32_e32 v141, v141
	v_rcp_f32_e32 v254, v254
	v_mul_f32_e32 v134, v3, v138
	v_mul_f32_e32 v135, v4, v211
	v_mul_f32_e32 v136, v159, v139
	v_mul_f32_e32 v137, v190, v252
	v_mul_f32_e32 v138, v191, v140
	v_mul_f32_e32 v139, v203, v253
	v_mul_f32_e32 v140, v204, v141
	v_mul_f32_e32 v141, v205, v254
	v_pk_mul_f32 v[74:75], v[74:75], v[134:135]
	v_pk_mul_f32 v[76:77], v[76:77], v[136:137]
	v_pk_mul_f32 v[70:71], v[70:71], v[138:139]
	v_pk_mul_f32 v[72:73], v[72:73], v[140:141]
	s_add_u32 s32, s38, 0x2c3000
	s_addc_u32 s33, s39, 0
	global_load_dwordx4 v[134:137], v248, s[32:33]
	s_add_u32 s32, s38, 0x2c2000
	s_addc_u32 s33, s39, 0
	global_load_dwordx4 v[138:141], v248, s[32:33]
	s_waitcnt vmcnt(12)
	v_lshlrev_b32_e32 v3, 16, v142
	v_and_b32_e32 v4, s74, v142
	v_lshlrev_b32_e32 v159, 16, v143
	v_and_b32_e32 v190, s74, v143
	v_lshlrev_b32_e32 v191, 16, v144
	v_and_b32_e32 v203, s74, v144
	v_lshlrev_b32_e32 v204, 16, v145
	v_and_b32_e32 v205, s74, v145
	v_max_f32_e32 v3, v3, v3
	v_max_f32_e32 v4, v4, v4
	v_max_f32_e32 v159, v159, v159
	v_max_f32_e32 v190, v190, v190
	v_max_f32_e32 v191, v191, v191
	v_max_f32_e32 v203, v203, v203
	v_max_f32_e32 v204, v204, v204
	v_max_f32_e32 v205, v205, v205
	v_max_f32_e32 v3, 0xc1f00000, v3
	v_max_f32_e32 v4, 0xc1f00000, v4
	v_max_f32_e32 v159, 0xc1f00000, v159
	v_max_f32_e32 v190, 0xc1f00000, v190
	v_max_f32_e32 v191, 0xc1f00000, v191
	v_max_f32_e32 v203, 0xc1f00000, v203
	v_max_f32_e32 v204, 0xc1f00000, v204
	v_max_f32_e32 v205, 0xc1f00000, v205
	v_mul_f32_e32 v3, 0xbfb8aa3b, v3
	v_mul_f32_e32 v4, 0xbfb8aa3b, v4
	v_mul_f32_e32 v159, 0xbfb8aa3b, v159
	v_mul_f32_e32 v190, 0xbfb8aa3b, v190
	v_mul_f32_e32 v191, 0xbfb8aa3b, v191
	v_mul_f32_e32 v203, 0xbfb8aa3b, v203
	v_mul_f32_e32 v204, 0xbfb8aa3b, v204
	v_mul_f32_e32 v205, 0xbfb8aa3b, v205
	v_exp_f32_e32 v3, v3
	v_exp_f32_e32 v4, v4
	v_exp_f32_e32 v159, v159
	v_exp_f32_e32 v190, v190
	v_exp_f32_e32 v191, v191
	v_exp_f32_e32 v203, v203
	v_exp_f32_e32 v204, v204
	v_exp_f32_e32 v205, v205
	v_add_f32_e32 v3, 1.0, v3
	v_add_f32_e32 v4, 1.0, v4
	v_add_f32_e32 v159, 1.0, v159
	v_add_f32_e32 v190, 1.0, v190
	v_add_f32_e32 v191, 1.0, v191
	v_add_f32_e32 v203, 1.0, v203
	v_add_f32_e32 v204, 1.0, v204
	v_add_f32_e32 v205, 1.0, v205
	v_and_b32_e32 v211, s74, v146
	v_lshlrev_b32_e32 v146, 16, v146
	v_and_b32_e32 v252, s74, v147
	v_lshlrev_b32_e32 v147, 16, v147
	v_and_b32_e32 v253, s74, v148
	v_lshlrev_b32_e32 v148, 16, v148
	v_and_b32_e32 v254, s74, v149
	v_lshlrev_b32_e32 v149, 16, v149
	v_mul_f32_e32 v146, 0xbfb8aa3b, v146
	v_mul_f32_e32 v211, 0xbfb8aa3b, v211
	v_mul_f32_e32 v147, 0xbfb8aa3b, v147
	v_mul_f32_e32 v252, 0xbfb8aa3b, v252
	v_mul_f32_e32 v148, 0xbfb8aa3b, v148
	v_mul_f32_e32 v253, 0xbfb8aa3b, v253
	v_mul_f32_e32 v149, 0xbfb8aa3b, v149
	v_mul_f32_e32 v254, 0xbfb8aa3b, v254
	v_exp_f32_e32 v146, v146
	v_exp_f32_e32 v211, v211
	v_exp_f32_e32 v147, v147
	v_exp_f32_e32 v252, v252
	v_exp_f32_e32 v148, v148
	v_exp_f32_e32 v253, v253
	v_exp_f32_e32 v149, v149
	v_exp_f32_e32 v254, v254
	v_add_f32_e32 v146, 1.0, v146
	v_add_f32_e32 v211, 1.0, v211
	v_add_f32_e32 v147, 1.0, v147
	v_add_f32_e32 v252, 1.0, v252
	v_add_f32_e32 v148, 1.0, v148
	v_add_f32_e32 v253, 1.0, v253
	v_add_f32_e32 v149, 1.0, v149
	v_add_f32_e32 v254, 1.0, v254
	v_rcp_f32_e32 v146, v146
	v_rcp_f32_e32 v211, v211
	v_rcp_f32_e32 v147, v147
	v_rcp_f32_e32 v252, v252
	v_rcp_f32_e32 v148, v148
	v_rcp_f32_e32 v253, v253
	v_rcp_f32_e32 v149, v149
	v_rcp_f32_e32 v254, v254
	v_mul_f32_e32 v142, v3, v146
	v_mul_f32_e32 v143, v4, v211
	v_mul_f32_e32 v144, v159, v147
	v_mul_f32_e32 v145, v190, v252
	v_mul_f32_e32 v146, v191, v148
	v_mul_f32_e32 v147, v203, v253
	v_mul_f32_e32 v148, v204, v149
	v_mul_f32_e32 v149, v205, v254
	v_pk_mul_f32 v[66:67], v[66:67], v[142:143]
	v_pk_mul_f32 v[68:69], v[68:69], v[144:145]
	v_pk_mul_f32 v[62:63], v[62:63], v[146:147]
	v_pk_mul_f32 v[64:65], v[64:65], v[148:149]
	s_add_u32 s32, s38, 0x2c3100
	s_addc_u32 s33, s39, 0
	global_load_dwordx4 v[142:145], v248, s[32:33]
	s_add_u32 s32, s38, 0x2c2100
	s_addc_u32 s33, s39, 0
	global_load_dwordx4 v[146:149], v248, s[32:33]
	s_waitcnt vmcnt(12)
	v_lshlrev_b32_e32 v3, 16, v180
	v_and_b32_e32 v4, s74, v180
	v_lshlrev_b32_e32 v159, 16, v181
	v_and_b32_e32 v190, s74, v181
	v_lshlrev_b32_e32 v191, 16, v182
	v_and_b32_e32 v203, s74, v182
	v_lshlrev_b32_e32 v204, 16, v183
	v_and_b32_e32 v205, s74, v183
	v_max_f32_e32 v3, v3, v3
	v_max_f32_e32 v4, v4, v4
	v_max_f32_e32 v159, v159, v159
	v_max_f32_e32 v190, v190, v190
	v_max_f32_e32 v191, v191, v191
	v_max_f32_e32 v203, v203, v203
	v_max_f32_e32 v204, v204, v204
	v_max_f32_e32 v205, v205, v205
	v_max_f32_e32 v3, 0xc1f00000, v3
	v_max_f32_e32 v4, 0xc1f00000, v4
	v_max_f32_e32 v159, 0xc1f00000, v159
	v_max_f32_e32 v190, 0xc1f00000, v190
	v_max_f32_e32 v191, 0xc1f00000, v191
	v_max_f32_e32 v203, 0xc1f00000, v203
	v_max_f32_e32 v204, 0xc1f00000, v204
	v_max_f32_e32 v205, 0xc1f00000, v205
	v_mul_f32_e32 v3, 0xbfb8aa3b, v3
	v_mul_f32_e32 v4, 0xbfb8aa3b, v4
	v_mul_f32_e32 v159, 0xbfb8aa3b, v159
	v_mul_f32_e32 v190, 0xbfb8aa3b, v190
	v_mul_f32_e32 v191, 0xbfb8aa3b, v191
	v_mul_f32_e32 v203, 0xbfb8aa3b, v203
	v_mul_f32_e32 v204, 0xbfb8aa3b, v204
	v_mul_f32_e32 v205, 0xbfb8aa3b, v205
	v_exp_f32_e32 v3, v3
	v_exp_f32_e32 v4, v4
	v_exp_f32_e32 v159, v159
	v_exp_f32_e32 v190, v190
	v_exp_f32_e32 v191, v191
	v_exp_f32_e32 v203, v203
	v_exp_f32_e32 v204, v204
	v_exp_f32_e32 v205, v205
	v_add_f32_e32 v3, 1.0, v3
	v_add_f32_e32 v4, 1.0, v4
	v_add_f32_e32 v159, 1.0, v159
	v_add_f32_e32 v190, 1.0, v190
	v_add_f32_e32 v191, 1.0, v191
	v_add_f32_e32 v203, 1.0, v203
	v_add_f32_e32 v204, 1.0, v204
	v_add_f32_e32 v205, 1.0, v205
	v_and_b32_e32 v211, s74, v186
	v_lshlrev_b32_e32 v186, 16, v186
	v_and_b32_e32 v252, s74, v187
	v_lshlrev_b32_e32 v187, 16, v187
	v_and_b32_e32 v253, s74, v188
	v_lshlrev_b32_e32 v188, 16, v188
	v_and_b32_e32 v254, s74, v189
	v_lshlrev_b32_e32 v189, 16, v189
	v_mul_f32_e32 v186, 0xbfb8aa3b, v186
	v_mul_f32_e32 v211, 0xbfb8aa3b, v211
	v_mul_f32_e32 v187, 0xbfb8aa3b, v187
	v_mul_f32_e32 v252, 0xbfb8aa3b, v252
	v_mul_f32_e32 v188, 0xbfb8aa3b, v188
	v_mul_f32_e32 v253, 0xbfb8aa3b, v253
	v_mul_f32_e32 v189, 0xbfb8aa3b, v189
	v_mul_f32_e32 v254, 0xbfb8aa3b, v254
	v_exp_f32_e32 v186, v186
	v_exp_f32_e32 v211, v211
	v_exp_f32_e32 v187, v187
	v_exp_f32_e32 v252, v252
	v_exp_f32_e32 v188, v188
	v_exp_f32_e32 v253, v253
	v_exp_f32_e32 v189, v189
	v_exp_f32_e32 v254, v254
	v_add_f32_e32 v186, 1.0, v186
	v_add_f32_e32 v211, 1.0, v211
	v_add_f32_e32 v187, 1.0, v187
	v_add_f32_e32 v252, 1.0, v252
	v_add_f32_e32 v188, 1.0, v188
	v_add_f32_e32 v253, 1.0, v253
	v_add_f32_e32 v189, 1.0, v189
	v_add_f32_e32 v254, 1.0, v254
	v_rcp_f32_e32 v186, v186
	v_rcp_f32_e32 v211, v211
	v_rcp_f32_e32 v187, v187
	v_rcp_f32_e32 v252, v252
	v_rcp_f32_e32 v188, v188
	v_rcp_f32_e32 v253, v253
	v_rcp_f32_e32 v189, v189
	v_rcp_f32_e32 v254, v254
	v_mul_f32_e32 v180, v3, v186
	v_mul_f32_e32 v181, v4, v211
	v_mul_f32_e32 v182, v159, v187
	v_mul_f32_e32 v183, v190, v252
	v_mul_f32_e32 v186, v191, v188
	v_mul_f32_e32 v187, v203, v253
	v_mul_f32_e32 v188, v204, v189
	v_mul_f32_e32 v189, v205, v254
	v_pk_mul_f32 v[34:35], v[34:35], v[180:181]
	v_pk_mul_f32 v[36:37], v[36:37], v[182:183]
	v_pk_mul_f32 v[30:31], v[30:31], v[186:187]
	v_pk_mul_f32 v[32:33], v[32:33], v[188:189]
	s_waitcnt vmcnt(10)
	v_lshlrev_b32_e32 v3, 16, v212
	v_and_b32_e32 v4, s74, v212
	v_lshlrev_b32_e32 v159, 16, v213
	v_and_b32_e32 v190, s74, v213
	v_lshlrev_b32_e32 v191, 16, v214
	v_and_b32_e32 v203, s74, v214
	v_lshlrev_b32_e32 v204, 16, v215
	v_and_b32_e32 v205, s74, v215
	v_max_f32_e32 v3, v3, v3
	v_max_f32_e32 v4, v4, v4
	v_max_f32_e32 v159, v159, v159
	v_max_f32_e32 v190, v190, v190
	v_max_f32_e32 v191, v191, v191
	v_max_f32_e32 v203, v203, v203
	v_max_f32_e32 v204, v204, v204
	v_max_f32_e32 v205, v205, v205
	v_max_f32_e32 v3, 0xc1f00000, v3
	v_max_f32_e32 v4, 0xc1f00000, v4
	v_max_f32_e32 v159, 0xc1f00000, v159
	v_max_f32_e32 v190, 0xc1f00000, v190
	v_max_f32_e32 v191, 0xc1f00000, v191
	v_max_f32_e32 v203, 0xc1f00000, v203
	v_max_f32_e32 v204, 0xc1f00000, v204
	v_max_f32_e32 v205, 0xc1f00000, v205
	v_mul_f32_e32 v3, 0xbfb8aa3b, v3
	v_mul_f32_e32 v4, 0xbfb8aa3b, v4
	v_mul_f32_e32 v159, 0xbfb8aa3b, v159
	v_mul_f32_e32 v190, 0xbfb8aa3b, v190
	v_mul_f32_e32 v191, 0xbfb8aa3b, v191
	v_mul_f32_e32 v203, 0xbfb8aa3b, v203
	v_mul_f32_e32 v204, 0xbfb8aa3b, v204
	v_mul_f32_e32 v205, 0xbfb8aa3b, v205
	v_exp_f32_e32 v3, v3
	v_exp_f32_e32 v4, v4
	v_exp_f32_e32 v159, v159
	v_exp_f32_e32 v190, v190
	v_exp_f32_e32 v191, v191
	v_exp_f32_e32 v203, v203
	v_exp_f32_e32 v204, v204
	v_exp_f32_e32 v205, v205
	v_add_f32_e32 v3, 1.0, v3
	v_add_f32_e32 v4, 1.0, v4
	v_add_f32_e32 v159, 1.0, v159
	v_add_f32_e32 v190, 1.0, v190
	v_add_f32_e32 v191, 1.0, v191
	v_add_f32_e32 v203, 1.0, v203
	v_add_f32_e32 v204, 1.0, v204
	v_add_f32_e32 v205, 1.0, v205
	v_and_b32_e32 v211, s74, v216
	v_lshlrev_b32_e32 v216, 16, v216
	v_and_b32_e32 v252, s74, v217
	v_lshlrev_b32_e32 v217, 16, v217
	v_and_b32_e32 v253, s74, v218
	v_lshlrev_b32_e32 v218, 16, v218
	v_and_b32_e32 v254, s74, v219
	v_lshlrev_b32_e32 v219, 16, v219
	v_mul_f32_e32 v216, 0xbfb8aa3b, v216
	v_mul_f32_e32 v211, 0xbfb8aa3b, v211
	v_mul_f32_e32 v217, 0xbfb8aa3b, v217
	v_mul_f32_e32 v252, 0xbfb8aa3b, v252
	v_mul_f32_e32 v218, 0xbfb8aa3b, v218
	v_mul_f32_e32 v253, 0xbfb8aa3b, v253
	v_mul_f32_e32 v219, 0xbfb8aa3b, v219
	v_mul_f32_e32 v254, 0xbfb8aa3b, v254
	v_exp_f32_e32 v216, v216
	v_exp_f32_e32 v211, v211
	v_exp_f32_e32 v217, v217
	v_exp_f32_e32 v252, v252
	v_exp_f32_e32 v218, v218
	v_exp_f32_e32 v253, v253
	v_exp_f32_e32 v219, v219
	v_exp_f32_e32 v254, v254
	v_add_f32_e32 v216, 1.0, v216
	v_add_f32_e32 v211, 1.0, v211
	v_add_f32_e32 v217, 1.0, v217
	v_add_f32_e32 v252, 1.0, v252
	v_add_f32_e32 v218, 1.0, v218
	v_add_f32_e32 v253, 1.0, v253
	v_add_f32_e32 v219, 1.0, v219
	v_add_f32_e32 v254, 1.0, v254
	v_rcp_f32_e32 v216, v216
	v_rcp_f32_e32 v211, v211
	v_rcp_f32_e32 v217, v217
	v_rcp_f32_e32 v252, v252
	v_rcp_f32_e32 v218, v218
	v_rcp_f32_e32 v253, v253
	v_rcp_f32_e32 v219, v219
	v_rcp_f32_e32 v254, v254
	v_mul_f32_e32 v212, v3, v216
	v_mul_f32_e32 v213, v4, v211
	v_mul_f32_e32 v214, v159, v217
	v_mul_f32_e32 v215, v190, v252
	v_mul_f32_e32 v216, v191, v218
	v_mul_f32_e32 v217, v203, v253
	v_mul_f32_e32 v218, v204, v219
	v_mul_f32_e32 v219, v205, v254
	v_pk_mul_f32 v[58:59], v[58:59], v[212:213]
	v_pk_mul_f32 v[60:61], v[60:61], v[214:215]
	v_pk_mul_f32 v[54:55], v[54:55], v[216:217]
	v_pk_mul_f32 v[56:57], v[56:57], v[218:219]
	s_waitcnt vmcnt(8)
	v_lshlrev_b32_e32 v3, 16, v220
	v_and_b32_e32 v4, s74, v220
	v_lshlrev_b32_e32 v159, 16, v221
	v_and_b32_e32 v190, s74, v221
	v_lshlrev_b32_e32 v191, 16, v222
	v_and_b32_e32 v203, s74, v222
	v_lshlrev_b32_e32 v204, 16, v223
	v_and_b32_e32 v205, s74, v223
	v_max_f32_e32 v3, v3, v3
	v_max_f32_e32 v4, v4, v4
	v_max_f32_e32 v159, v159, v159
	v_max_f32_e32 v190, v190, v190
	v_max_f32_e32 v191, v191, v191
	v_max_f32_e32 v203, v203, v203
	v_max_f32_e32 v204, v204, v204
	v_max_f32_e32 v205, v205, v205
	v_max_f32_e32 v3, 0xc1f00000, v3
	v_max_f32_e32 v4, 0xc1f00000, v4
	v_max_f32_e32 v159, 0xc1f00000, v159
	v_max_f32_e32 v190, 0xc1f00000, v190
	v_max_f32_e32 v191, 0xc1f00000, v191
	v_max_f32_e32 v203, 0xc1f00000, v203
	v_max_f32_e32 v204, 0xc1f00000, v204
	v_max_f32_e32 v205, 0xc1f00000, v205
	v_mul_f32_e32 v3, 0xbfb8aa3b, v3
	v_mul_f32_e32 v4, 0xbfb8aa3b, v4
	v_mul_f32_e32 v159, 0xbfb8aa3b, v159
	v_mul_f32_e32 v190, 0xbfb8aa3b, v190
	v_mul_f32_e32 v191, 0xbfb8aa3b, v191
	v_mul_f32_e32 v203, 0xbfb8aa3b, v203
	v_mul_f32_e32 v204, 0xbfb8aa3b, v204
	v_mul_f32_e32 v205, 0xbfb8aa3b, v205
	v_exp_f32_e32 v3, v3
	v_exp_f32_e32 v4, v4
	v_exp_f32_e32 v159, v159
	v_exp_f32_e32 v190, v190
	v_exp_f32_e32 v191, v191
	v_exp_f32_e32 v203, v203
	v_exp_f32_e32 v204, v204
	v_exp_f32_e32 v205, v205
	v_add_f32_e32 v3, 1.0, v3
	v_add_f32_e32 v4, 1.0, v4
	v_add_f32_e32 v159, 1.0, v159
	v_add_f32_e32 v190, 1.0, v190
	v_add_f32_e32 v191, 1.0, v191
	v_add_f32_e32 v203, 1.0, v203
	v_add_f32_e32 v204, 1.0, v204
	v_add_f32_e32 v205, 1.0, v205
	v_and_b32_e32 v211, s74, v224
	v_lshlrev_b32_e32 v224, 16, v224
	v_and_b32_e32 v252, s74, v225
	v_lshlrev_b32_e32 v225, 16, v225
	v_and_b32_e32 v253, s74, v226
	v_lshlrev_b32_e32 v226, 16, v226
	v_and_b32_e32 v254, s74, v227
	v_lshlrev_b32_e32 v227, 16, v227
	v_mul_f32_e32 v224, 0xbfb8aa3b, v224
	v_mul_f32_e32 v211, 0xbfb8aa3b, v211
	v_mul_f32_e32 v225, 0xbfb8aa3b, v225
	v_mul_f32_e32 v252, 0xbfb8aa3b, v252
	v_mul_f32_e32 v226, 0xbfb8aa3b, v226
	v_mul_f32_e32 v253, 0xbfb8aa3b, v253
	v_mul_f32_e32 v227, 0xbfb8aa3b, v227
	v_mul_f32_e32 v254, 0xbfb8aa3b, v254
	v_exp_f32_e32 v224, v224
	v_exp_f32_e32 v211, v211
	v_exp_f32_e32 v225, v225
	v_exp_f32_e32 v252, v252
	v_exp_f32_e32 v226, v226
	v_exp_f32_e32 v253, v253
	v_exp_f32_e32 v227, v227
	v_exp_f32_e32 v254, v254
	v_add_f32_e32 v224, 1.0, v224
	v_add_f32_e32 v211, 1.0, v211
	v_add_f32_e32 v225, 1.0, v225
	v_add_f32_e32 v252, 1.0, v252
	v_add_f32_e32 v226, 1.0, v226
	v_add_f32_e32 v253, 1.0, v253
	v_add_f32_e32 v227, 1.0, v227
	v_add_f32_e32 v254, 1.0, v254
	v_rcp_f32_e32 v224, v224
	v_rcp_f32_e32 v211, v211
	v_rcp_f32_e32 v225, v225
	v_rcp_f32_e32 v252, v252
	v_rcp_f32_e32 v226, v226
	v_rcp_f32_e32 v253, v253
	v_rcp_f32_e32 v227, v227
	v_rcp_f32_e32 v254, v254
	v_mul_f32_e32 v220, v3, v224
	v_mul_f32_e32 v221, v4, v211
	v_mul_f32_e32 v222, v159, v225
	v_mul_f32_e32 v223, v190, v252
	v_mul_f32_e32 v224, v191, v226
	v_mul_f32_e32 v225, v203, v253
	v_mul_f32_e32 v226, v204, v227
	v_mul_f32_e32 v227, v205, v254
	v_pk_mul_f32 v[26:27], v[26:27], v[220:221]
	v_pk_mul_f32 v[28:29], v[28:29], v[222:223]
	v_pk_mul_f32 v[22:23], v[22:23], v[224:225]
	v_pk_mul_f32 v[24:25], v[24:25], v[226:227]
	s_waitcnt vmcnt(6)
	v_lshlrev_b32_e32 v3, 16, v228
	v_and_b32_e32 v4, s74, v228
	v_lshlrev_b32_e32 v159, 16, v229
	v_and_b32_e32 v190, s74, v229
	v_lshlrev_b32_e32 v191, 16, v230
	v_and_b32_e32 v203, s74, v230
	v_lshlrev_b32_e32 v204, 16, v231
	v_and_b32_e32 v205, s74, v231
	v_max_f32_e32 v3, v3, v3
	v_max_f32_e32 v4, v4, v4
	v_max_f32_e32 v159, v159, v159
	v_max_f32_e32 v190, v190, v190
	v_max_f32_e32 v191, v191, v191
	v_max_f32_e32 v203, v203, v203
	v_max_f32_e32 v204, v204, v204
	v_max_f32_e32 v205, v205, v205
	v_max_f32_e32 v3, 0xc1f00000, v3
	v_max_f32_e32 v4, 0xc1f00000, v4
	v_max_f32_e32 v159, 0xc1f00000, v159
	v_max_f32_e32 v190, 0xc1f00000, v190
	v_max_f32_e32 v191, 0xc1f00000, v191
	v_max_f32_e32 v203, 0xc1f00000, v203
	v_max_f32_e32 v204, 0xc1f00000, v204
	v_max_f32_e32 v205, 0xc1f00000, v205
	v_mul_f32_e32 v3, 0xbfb8aa3b, v3
	v_mul_f32_e32 v4, 0xbfb8aa3b, v4
	v_mul_f32_e32 v159, 0xbfb8aa3b, v159
	v_mul_f32_e32 v190, 0xbfb8aa3b, v190
	v_mul_f32_e32 v191, 0xbfb8aa3b, v191
	v_mul_f32_e32 v203, 0xbfb8aa3b, v203
	v_mul_f32_e32 v204, 0xbfb8aa3b, v204
	v_mul_f32_e32 v205, 0xbfb8aa3b, v205
	v_exp_f32_e32 v3, v3
	v_exp_f32_e32 v4, v4
	v_exp_f32_e32 v159, v159
	v_exp_f32_e32 v190, v190
	v_exp_f32_e32 v191, v191
	v_exp_f32_e32 v203, v203
	v_exp_f32_e32 v204, v204
	v_exp_f32_e32 v205, v205
	v_add_f32_e32 v3, 1.0, v3
	v_add_f32_e32 v4, 1.0, v4
	v_add_f32_e32 v159, 1.0, v159
	v_add_f32_e32 v190, 1.0, v190
	v_add_f32_e32 v191, 1.0, v191
	v_add_f32_e32 v203, 1.0, v203
	v_add_f32_e32 v204, 1.0, v204
	v_add_f32_e32 v205, 1.0, v205
	v_and_b32_e32 v211, s74, v232
	v_lshlrev_b32_e32 v232, 16, v232
	v_and_b32_e32 v252, s74, v233
	v_lshlrev_b32_e32 v233, 16, v233
	v_and_b32_e32 v253, s74, v234
	v_lshlrev_b32_e32 v234, 16, v234
	v_and_b32_e32 v254, s74, v235
	v_lshlrev_b32_e32 v235, 16, v235
	v_mul_f32_e32 v232, 0xbfb8aa3b, v232
	v_mul_f32_e32 v211, 0xbfb8aa3b, v211
	v_mul_f32_e32 v233, 0xbfb8aa3b, v233
	v_mul_f32_e32 v252, 0xbfb8aa3b, v252
	v_mul_f32_e32 v234, 0xbfb8aa3b, v234
	v_mul_f32_e32 v253, 0xbfb8aa3b, v253
	v_mul_f32_e32 v235, 0xbfb8aa3b, v235
	v_mul_f32_e32 v254, 0xbfb8aa3b, v254
	v_exp_f32_e32 v232, v232
	v_exp_f32_e32 v211, v211
	v_exp_f32_e32 v233, v233
	v_exp_f32_e32 v252, v252
	v_exp_f32_e32 v234, v234
	v_exp_f32_e32 v253, v253
	v_exp_f32_e32 v235, v235
	v_exp_f32_e32 v254, v254
	v_add_f32_e32 v232, 1.0, v232
	v_add_f32_e32 v211, 1.0, v211
	v_add_f32_e32 v233, 1.0, v233
	v_add_f32_e32 v252, 1.0, v252
	v_add_f32_e32 v234, 1.0, v234
	v_add_f32_e32 v253, 1.0, v253
	v_add_f32_e32 v235, 1.0, v235
	v_add_f32_e32 v254, 1.0, v254
	v_rcp_f32_e32 v232, v232
	v_rcp_f32_e32 v211, v211
	v_rcp_f32_e32 v233, v233
	v_rcp_f32_e32 v252, v252
	v_rcp_f32_e32 v234, v234
	v_rcp_f32_e32 v253, v253
	v_rcp_f32_e32 v235, v235
	v_rcp_f32_e32 v254, v254
	v_mul_f32_e32 v228, v3, v232
	v_mul_f32_e32 v229, v4, v211
	v_mul_f32_e32 v230, v159, v233
	v_mul_f32_e32 v231, v190, v252
	v_mul_f32_e32 v232, v191, v234
	v_mul_f32_e32 v233, v203, v253
	v_mul_f32_e32 v234, v204, v235
	v_mul_f32_e32 v235, v205, v254
	v_pk_mul_f32 v[50:51], v[50:51], v[228:229]
	v_pk_mul_f32 v[52:53], v[52:53], v[230:231]
	v_pk_mul_f32 v[46:47], v[46:47], v[232:233]
	v_pk_mul_f32 v[48:49], v[48:49], v[234:235]
	s_waitcnt vmcnt(4)
	v_lshlrev_b32_e32 v3, 16, v236
	v_and_b32_e32 v4, s74, v236
	v_lshlrev_b32_e32 v159, 16, v237
	v_and_b32_e32 v190, s74, v237
	v_lshlrev_b32_e32 v191, 16, v238
	v_and_b32_e32 v203, s74, v238
	v_lshlrev_b32_e32 v204, 16, v239
	v_and_b32_e32 v205, s74, v239
	v_max_f32_e32 v3, v3, v3
	v_max_f32_e32 v4, v4, v4
	v_max_f32_e32 v159, v159, v159
	v_max_f32_e32 v190, v190, v190
	v_max_f32_e32 v191, v191, v191
	v_max_f32_e32 v203, v203, v203
	v_max_f32_e32 v204, v204, v204
	v_max_f32_e32 v205, v205, v205
	v_max_f32_e32 v3, 0xc1f00000, v3
	v_max_f32_e32 v4, 0xc1f00000, v4
	v_max_f32_e32 v159, 0xc1f00000, v159
	v_max_f32_e32 v190, 0xc1f00000, v190
	v_max_f32_e32 v191, 0xc1f00000, v191
	v_max_f32_e32 v203, 0xc1f00000, v203
	v_max_f32_e32 v204, 0xc1f00000, v204
	v_max_f32_e32 v205, 0xc1f00000, v205
	v_mul_f32_e32 v3, 0xbfb8aa3b, v3
	v_mul_f32_e32 v4, 0xbfb8aa3b, v4
	v_mul_f32_e32 v159, 0xbfb8aa3b, v159
	v_mul_f32_e32 v190, 0xbfb8aa3b, v190
	v_mul_f32_e32 v191, 0xbfb8aa3b, v191
	v_mul_f32_e32 v203, 0xbfb8aa3b, v203
	v_mul_f32_e32 v204, 0xbfb8aa3b, v204
	v_mul_f32_e32 v205, 0xbfb8aa3b, v205
	v_exp_f32_e32 v3, v3
	v_exp_f32_e32 v4, v4
	v_exp_f32_e32 v159, v159
	v_exp_f32_e32 v190, v190
	v_exp_f32_e32 v191, v191
	v_exp_f32_e32 v203, v203
	v_exp_f32_e32 v204, v204
	v_exp_f32_e32 v205, v205
	v_add_f32_e32 v3, 1.0, v3
	v_add_f32_e32 v4, 1.0, v4
	v_add_f32_e32 v159, 1.0, v159
	v_add_f32_e32 v190, 1.0, v190
	v_add_f32_e32 v191, 1.0, v191
	v_add_f32_e32 v203, 1.0, v203
	v_add_f32_e32 v204, 1.0, v204
	v_add_f32_e32 v205, 1.0, v205
	v_and_b32_e32 v211, s74, v240
	v_lshlrev_b32_e32 v240, 16, v240
	v_and_b32_e32 v252, s74, v241
	v_lshlrev_b32_e32 v241, 16, v241
	v_and_b32_e32 v253, s74, v242
	v_lshlrev_b32_e32 v242, 16, v242
	v_and_b32_e32 v254, s74, v243
	v_lshlrev_b32_e32 v243, 16, v243
	v_mul_f32_e32 v240, 0xbfb8aa3b, v240
	v_mul_f32_e32 v211, 0xbfb8aa3b, v211
	v_mul_f32_e32 v241, 0xbfb8aa3b, v241
	v_mul_f32_e32 v252, 0xbfb8aa3b, v252
	v_mul_f32_e32 v242, 0xbfb8aa3b, v242
	v_mul_f32_e32 v253, 0xbfb8aa3b, v253
	v_mul_f32_e32 v243, 0xbfb8aa3b, v243
	v_mul_f32_e32 v254, 0xbfb8aa3b, v254
	v_exp_f32_e32 v240, v240
	v_exp_f32_e32 v211, v211
	v_exp_f32_e32 v241, v241
	v_exp_f32_e32 v252, v252
	v_exp_f32_e32 v242, v242
	v_exp_f32_e32 v253, v253
	v_exp_f32_e32 v243, v243
	v_exp_f32_e32 v254, v254
	v_add_f32_e32 v240, 1.0, v240
	v_add_f32_e32 v211, 1.0, v211
	v_add_f32_e32 v241, 1.0, v241
	v_add_f32_e32 v252, 1.0, v252
	v_add_f32_e32 v242, 1.0, v242
	v_add_f32_e32 v253, 1.0, v253
	v_add_f32_e32 v243, 1.0, v243
	v_add_f32_e32 v254, 1.0, v254
	v_rcp_f32_e32 v240, v240
	v_rcp_f32_e32 v211, v211
	v_rcp_f32_e32 v241, v241
	v_rcp_f32_e32 v252, v252
	v_rcp_f32_e32 v242, v242
	v_rcp_f32_e32 v253, v253
	v_rcp_f32_e32 v243, v243
	v_rcp_f32_e32 v254, v254
	v_mul_f32_e32 v236, v3, v240
	v_mul_f32_e32 v237, v4, v211
	v_mul_f32_e32 v238, v159, v241
	v_mul_f32_e32 v239, v190, v252
	v_mul_f32_e32 v240, v191, v242
	v_mul_f32_e32 v241, v203, v253
	v_mul_f32_e32 v242, v204, v243
	v_mul_f32_e32 v243, v205, v254
	v_pk_mul_f32 v[18:19], v[18:19], v[236:237]
	v_pk_mul_f32 v[20:21], v[20:21], v[238:239]
	v_pk_mul_f32 v[14:15], v[14:15], v[240:241]
	v_pk_mul_f32 v[16:17], v[16:17], v[242:243]
	s_waitcnt vmcnt(2)
	v_lshlrev_b32_e32 v3, 16, v134
	v_and_b32_e32 v4, s74, v134
	v_lshlrev_b32_e32 v159, 16, v135
	v_and_b32_e32 v190, s74, v135
	v_lshlrev_b32_e32 v191, 16, v136
	v_and_b32_e32 v203, s74, v136
	v_lshlrev_b32_e32 v204, 16, v137
	v_and_b32_e32 v205, s74, v137
	v_max_f32_e32 v3, v3, v3
	v_max_f32_e32 v4, v4, v4
	v_max_f32_e32 v159, v159, v159
	v_max_f32_e32 v190, v190, v190
	v_max_f32_e32 v191, v191, v191
	v_max_f32_e32 v203, v203, v203
	v_max_f32_e32 v204, v204, v204
	v_max_f32_e32 v205, v205, v205
	v_max_f32_e32 v3, 0xc1f00000, v3
	v_max_f32_e32 v4, 0xc1f00000, v4
	v_max_f32_e32 v159, 0xc1f00000, v159
	v_max_f32_e32 v190, 0xc1f00000, v190
	v_max_f32_e32 v191, 0xc1f00000, v191
	v_max_f32_e32 v203, 0xc1f00000, v203
	v_max_f32_e32 v204, 0xc1f00000, v204
	v_max_f32_e32 v205, 0xc1f00000, v205
	v_mul_f32_e32 v3, 0xbfb8aa3b, v3
	v_mul_f32_e32 v4, 0xbfb8aa3b, v4
	v_mul_f32_e32 v159, 0xbfb8aa3b, v159
	v_mul_f32_e32 v190, 0xbfb8aa3b, v190
	v_mul_f32_e32 v191, 0xbfb8aa3b, v191
	v_mul_f32_e32 v203, 0xbfb8aa3b, v203
	v_mul_f32_e32 v204, 0xbfb8aa3b, v204
	v_mul_f32_e32 v205, 0xbfb8aa3b, v205
	v_exp_f32_e32 v3, v3
	v_exp_f32_e32 v4, v4
	v_exp_f32_e32 v159, v159
	v_exp_f32_e32 v190, v190
	v_exp_f32_e32 v191, v191
	v_exp_f32_e32 v203, v203
	v_exp_f32_e32 v204, v204
	v_exp_f32_e32 v205, v205
	v_add_f32_e32 v3, 1.0, v3
	v_add_f32_e32 v4, 1.0, v4
	v_add_f32_e32 v159, 1.0, v159
	v_add_f32_e32 v190, 1.0, v190
	v_add_f32_e32 v191, 1.0, v191
	v_add_f32_e32 v203, 1.0, v203
	v_add_f32_e32 v204, 1.0, v204
	v_add_f32_e32 v205, 1.0, v205
	v_and_b32_e32 v211, s74, v138
	v_lshlrev_b32_e32 v138, 16, v138
	v_and_b32_e32 v252, s74, v139
	v_lshlrev_b32_e32 v139, 16, v139
	v_and_b32_e32 v253, s74, v140
	v_lshlrev_b32_e32 v140, 16, v140
	v_and_b32_e32 v254, s74, v141
	v_lshlrev_b32_e32 v141, 16, v141
	v_mul_f32_e32 v138, 0xbfb8aa3b, v138
	v_mul_f32_e32 v211, 0xbfb8aa3b, v211
	v_mul_f32_e32 v139, 0xbfb8aa3b, v139
	v_mul_f32_e32 v252, 0xbfb8aa3b, v252
	v_mul_f32_e32 v140, 0xbfb8aa3b, v140
	v_mul_f32_e32 v253, 0xbfb8aa3b, v253
	v_mul_f32_e32 v141, 0xbfb8aa3b, v141
	v_mul_f32_e32 v254, 0xbfb8aa3b, v254
	v_exp_f32_e32 v138, v138
	v_exp_f32_e32 v211, v211
	v_exp_f32_e32 v139, v139
	v_exp_f32_e32 v252, v252
	v_exp_f32_e32 v140, v140
	v_exp_f32_e32 v253, v253
	v_exp_f32_e32 v141, v141
	v_exp_f32_e32 v254, v254
	v_add_f32_e32 v138, 1.0, v138
	v_add_f32_e32 v211, 1.0, v211
	v_add_f32_e32 v139, 1.0, v139
	v_add_f32_e32 v252, 1.0, v252
	v_add_f32_e32 v140, 1.0, v140
	v_add_f32_e32 v253, 1.0, v253
	v_add_f32_e32 v141, 1.0, v141
	v_add_f32_e32 v254, 1.0, v254
	v_rcp_f32_e32 v138, v138
	v_rcp_f32_e32 v211, v211
	v_rcp_f32_e32 v139, v139
	v_rcp_f32_e32 v252, v252
	v_rcp_f32_e32 v140, v140
	v_rcp_f32_e32 v253, v253
	v_rcp_f32_e32 v141, v141
	v_rcp_f32_e32 v254, v254
	v_mul_f32_e32 v134, v3, v138
	v_mul_f32_e32 v135, v4, v211
	v_mul_f32_e32 v136, v159, v139
	v_mul_f32_e32 v137, v190, v252
	v_mul_f32_e32 v138, v191, v140
	v_mul_f32_e32 v139, v203, v253
	v_mul_f32_e32 v140, v204, v141
	v_mul_f32_e32 v141, v205, v254
	v_pk_mul_f32 v[42:43], v[42:43], v[134:135]
	v_pk_mul_f32 v[44:45], v[44:45], v[136:137]
	v_pk_mul_f32 v[38:39], v[38:39], v[138:139]
	v_pk_mul_f32 v[40:41], v[40:41], v[140:141]
	s_waitcnt vmcnt(0)
	v_lshlrev_b32_e32 v3, 16, v142
	v_and_b32_e32 v4, s74, v142
	v_lshlrev_b32_e32 v159, 16, v143
	v_and_b32_e32 v190, s74, v143
	v_lshlrev_b32_e32 v191, 16, v144
	v_and_b32_e32 v203, s74, v144
	v_lshlrev_b32_e32 v204, 16, v145
	v_and_b32_e32 v205, s74, v145
	v_max_f32_e32 v3, v3, v3
	v_max_f32_e32 v4, v4, v4
	v_max_f32_e32 v159, v159, v159
	v_max_f32_e32 v190, v190, v190
	v_max_f32_e32 v191, v191, v191
	v_max_f32_e32 v203, v203, v203
	v_max_f32_e32 v204, v204, v204
	v_max_f32_e32 v205, v205, v205
	v_max_f32_e32 v3, 0xc1f00000, v3
	v_max_f32_e32 v4, 0xc1f00000, v4
	v_max_f32_e32 v159, 0xc1f00000, v159
	v_max_f32_e32 v190, 0xc1f00000, v190
	v_max_f32_e32 v191, 0xc1f00000, v191
	v_max_f32_e32 v203, 0xc1f00000, v203
	v_max_f32_e32 v204, 0xc1f00000, v204
	v_max_f32_e32 v205, 0xc1f00000, v205
	v_mul_f32_e32 v3, 0xbfb8aa3b, v3
	v_mul_f32_e32 v4, 0xbfb8aa3b, v4
	v_mul_f32_e32 v159, 0xbfb8aa3b, v159
	v_mul_f32_e32 v190, 0xbfb8aa3b, v190
	v_mul_f32_e32 v191, 0xbfb8aa3b, v191
	v_mul_f32_e32 v203, 0xbfb8aa3b, v203
	v_mul_f32_e32 v204, 0xbfb8aa3b, v204
	v_mul_f32_e32 v205, 0xbfb8aa3b, v205
	v_exp_f32_e32 v3, v3
	v_exp_f32_e32 v4, v4
	v_exp_f32_e32 v159, v159
	v_exp_f32_e32 v190, v190
	v_exp_f32_e32 v191, v191
	v_exp_f32_e32 v203, v203
	v_exp_f32_e32 v204, v204
	v_exp_f32_e32 v205, v205
	v_add_f32_e32 v3, 1.0, v3
	v_add_f32_e32 v4, 1.0, v4
	v_add_f32_e32 v159, 1.0, v159
	v_add_f32_e32 v190, 1.0, v190
	v_add_f32_e32 v191, 1.0, v191
	v_add_f32_e32 v203, 1.0, v203
	v_add_f32_e32 v204, 1.0, v204
	v_add_f32_e32 v205, 1.0, v205
	v_and_b32_e32 v211, s74, v146
	v_lshlrev_b32_e32 v146, 16, v146
	v_and_b32_e32 v252, s74, v147
	v_lshlrev_b32_e32 v147, 16, v147
	v_and_b32_e32 v253, s74, v148
	v_lshlrev_b32_e32 v148, 16, v148
	v_and_b32_e32 v254, s74, v149
	v_lshlrev_b32_e32 v149, 16, v149
	v_mul_f32_e32 v146, 0xbfb8aa3b, v146
	v_mul_f32_e32 v211, 0xbfb8aa3b, v211
	v_mul_f32_e32 v147, 0xbfb8aa3b, v147
	v_mul_f32_e32 v252, 0xbfb8aa3b, v252
	v_mul_f32_e32 v148, 0xbfb8aa3b, v148
	v_mul_f32_e32 v253, 0xbfb8aa3b, v253
	v_mul_f32_e32 v149, 0xbfb8aa3b, v149
	v_mul_f32_e32 v254, 0xbfb8aa3b, v254
	v_exp_f32_e32 v146, v146
	v_exp_f32_e32 v211, v211
	v_exp_f32_e32 v147, v147
	v_exp_f32_e32 v252, v252
	v_exp_f32_e32 v148, v148
	v_exp_f32_e32 v253, v253
	v_exp_f32_e32 v149, v149
	v_exp_f32_e32 v254, v254
	v_add_f32_e32 v146, 1.0, v146
	v_add_f32_e32 v211, 1.0, v211
	v_add_f32_e32 v147, 1.0, v147
	v_add_f32_e32 v252, 1.0, v252
	v_add_f32_e32 v148, 1.0, v148
	v_add_f32_e32 v253, 1.0, v253
	v_add_f32_e32 v149, 1.0, v149
	v_add_f32_e32 v254, 1.0, v254
	v_rcp_f32_e32 v146, v146
	v_rcp_f32_e32 v211, v211
	v_rcp_f32_e32 v147, v147
	v_rcp_f32_e32 v252, v252
	v_rcp_f32_e32 v148, v148
	v_rcp_f32_e32 v253, v253
	v_rcp_f32_e32 v149, v149
	v_rcp_f32_e32 v254, v254
	v_mul_f32_e32 v142, v3, v146
	v_mul_f32_e32 v143, v4, v211
	v_mul_f32_e32 v144, v159, v147
	v_mul_f32_e32 v145, v190, v252
	v_mul_f32_e32 v146, v191, v148
	v_mul_f32_e32 v147, v203, v253
	v_mul_f32_e32 v148, v204, v149
	v_mul_f32_e32 v149, v205, v254
	v_pk_mul_f32 v[10:11], v[10:11], v[142:143]
	v_pk_mul_f32 v[12:13], v[12:13], v[144:145]
	v_pk_mul_f32 v[6:7], v[6:7], v[146:147]
	v_pk_mul_f32 v[8:9], v[8:9], v[148:149]
	s_branch .Lp4e_done
.Lp4e_g1:
	v_add_u32_e32 v253, s68, v151
	v_lshlrev_b32_e32 v211, 14, v253
	v_lshlrev_b32_e32 v252, 12, v253
	v_or_b32_e32 v253, s75, v155
	v_lshl_add_u32 v211, v253, 1, v211
	v_lshl_add_u32 v252, v253, 1, v252
	s_add_u32 s32, s38, 0x3000
	s_addc_u32 s33, s39, 0
	global_load_dwordx4 v[134:137], v211, s[32:33]
	s_add_u32 s32, s38, 0x3100
	s_addc_u32 s33, s39, 0
	global_load_dwordx4 v[138:141], v211, s[32:33]
	s_add_u32 s32, s38, 0x43000
	s_addc_u32 s33, s39, 0
	global_load_dwordx4 v[142:145], v211, s[32:33]
	s_add_u32 s32, s38, 0x43100
	s_addc_u32 s33, s39, 0
	global_load_dwordx4 v[146:149], v211, s[32:33]
	s_add_u32 s32, s38, 0x83000
	s_addc_u32 s33, s39, 0
	global_load_dwordx4 v[180:183], v211, s[32:33]
	s_add_u32 s32, s38, 0x83100
	s_addc_u32 s33, s39, 0
	global_load_dwordx4 v[186:189], v211, s[32:33]
	s_add_u32 s32, s38, 0xc3000
	s_addc_u32 s33, s39, 0
	global_load_dwordx4 v[212:215], v211, s[32:33]
	s_add_u32 s32, s38, 0xc3100
	s_addc_u32 s33, s39, 0
	global_load_dwordx4 v[216:219], v211, s[32:33]
	s_add_u32 s32, s38, 0x203000
	s_addc_u32 s33, s39, 0
	global_load_dwordx4 v[220:223], v211, s[32:33]
	s_add_u32 s32, s38, 0x203100
	s_addc_u32 s33, s39, 0
	global_load_dwordx4 v[224:227], v211, s[32:33]
	s_add_u32 s32, s38, 0x243000
	s_addc_u32 s33, s39, 0
	global_load_dwordx4 v[228:231], v211, s[32:33]
	s_add_u32 s32, s38, 0x243100
	s_addc_u32 s33, s39, 0
	global_load_dwordx4 v[232:235], v211, s[32:33]
	s_add_u32 s32, s38, 0x283000
	s_addc_u32 s33, s39, 0
	global_load_dwordx4 v[236:239], v211, s[32:33]
	s_add_u32 s32, s38, 0x283100
	s_addc_u32 s33, s39, 0
	global_load_dwordx4 v[240:243], v211, s[32:33]
	s_add_u32 s32, s38, 0x2c3000
	s_addc_u32 s33, s39, 0
	global_load_dwordx4 v[244:247], v211, s[32:33]
	s_add_u32 s32, s38, 0x2c3100
	s_addc_u32 s33, s39, 0
	global_load_dwordx4 v[248:251], v211, s[32:33]
	s_waitcnt vmcnt(15)
	v_lshlrev_b32_e32 v3, 16, v134
	v_and_b32_e32 v4, s74, v134
	v_lshlrev_b32_e32 v159, 16, v135
	v_and_b32_e32 v190, s74, v135
	v_lshlrev_b32_e32 v191, 16, v136
	v_and_b32_e32 v203, s74, v136
	v_lshlrev_b32_e32 v204, 16, v137
	v_and_b32_e32 v205, s74, v137
	v_max_f32_e32 v3, v3, v3
	v_max_f32_e32 v4, v4, v4
	v_max_f32_e32 v159, v159, v159
	v_max_f32_e32 v190, v190, v190
	v_max_f32_e32 v191, v191, v191
	v_max_f32_e32 v203, v203, v203
	v_max_f32_e32 v204, v204, v204
	v_max_f32_e32 v205, v205, v205
	v_max_f32_e32 v3, 0xc1f00000, v3
	v_max_f32_e32 v4, 0xc1f00000, v4
	v_max_f32_e32 v159, 0xc1f00000, v159
	v_max_f32_e32 v190, 0xc1f00000, v190
	v_max_f32_e32 v191, 0xc1f00000, v191
	v_max_f32_e32 v203, 0xc1f00000, v203
	v_max_f32_e32 v204, 0xc1f00000, v204
	v_max_f32_e32 v205, 0xc1f00000, v205
	v_mul_f32_e32 v3, 0xbfb8aa3b, v3
	v_mul_f32_e32 v4, 0xbfb8aa3b, v4
	v_mul_f32_e32 v159, 0xbfb8aa3b, v159
	v_mul_f32_e32 v190, 0xbfb8aa3b, v190
	v_mul_f32_e32 v191, 0xbfb8aa3b, v191
	v_mul_f32_e32 v203, 0xbfb8aa3b, v203
	v_mul_f32_e32 v204, 0xbfb8aa3b, v204
	v_mul_f32_e32 v205, 0xbfb8aa3b, v205
	v_exp_f32_e32 v3, v3
	v_exp_f32_e32 v4, v4
	v_exp_f32_e32 v159, v159
	v_exp_f32_e32 v190, v190
	v_exp_f32_e32 v191, v191
	v_exp_f32_e32 v203, v203
	v_exp_f32_e32 v204, v204
	v_exp_f32_e32 v205, v205
	v_add_f32_e32 v3, 1.0, v3
	v_add_f32_e32 v4, 1.0, v4
	v_add_f32_e32 v159, 1.0, v159
	v_add_f32_e32 v190, 1.0, v190
	v_add_f32_e32 v191, 1.0, v191
	v_add_f32_e32 v203, 1.0, v203
	v_add_f32_e32 v204, 1.0, v204
	v_add_f32_e32 v205, 1.0, v205
	v_rcp_f32_e32 v3, v3
	v_rcp_f32_e32 v4, v4
	v_rcp_f32_e32 v159, v159
	v_rcp_f32_e32 v190, v190
	v_rcp_f32_e32 v191, v191
	v_rcp_f32_e32 v203, v203
	v_rcp_f32_e32 v204, v204
	v_rcp_f32_e32 v205, v205
	v_mul_f32_e32 v3, v130, v3
	v_mul_f32_e32 v4, v131, v4
	v_mul_f32_e32 v159, v132, v159
	v_mul_f32_e32 v190, v133, v190
	v_mul_f32_e32 v191, v126, v191
	v_mul_f32_e32 v203, v127, v203
	v_mul_f32_e32 v204, v128, v204
	v_mul_f32_e32 v205, v129, v205
	v_cvt_pk_bf16_f32 v134, v3, v4
	v_cvt_pk_bf16_f32 v135, v159, v190
	v_cvt_pk_bf16_f32 v136, v191, v203
	v_cvt_pk_bf16_f32 v137, v204, v205
	s_add_u32 s32, s44, 0x0
	s_addc_u32 s33, s45, 0
	global_store_dwordx4 v252, v[134:137], s[32:33]
	s_waitcnt vmcnt(15)
	v_lshlrev_b32_e32 v3, 16, v138
	v_and_b32_e32 v4, s74, v138
	v_lshlrev_b32_e32 v159, 16, v139
	v_and_b32_e32 v190, s74, v139
	v_lshlrev_b32_e32 v191, 16, v140
	v_and_b32_e32 v203, s74, v140
	v_lshlrev_b32_e32 v204, 16, v141
	v_and_b32_e32 v205, s74, v141
	v_max_f32_e32 v3, v3, v3
	v_max_f32_e32 v4, v4, v4
	v_max_f32_e32 v159, v159, v159
	v_max_f32_e32 v190, v190, v190
	v_max_f32_e32 v191, v191, v191
	v_max_f32_e32 v203, v203, v203
	v_max_f32_e32 v204, v204, v204
	v_max_f32_e32 v205, v205, v205
	v_max_f32_e32 v3, 0xc1f00000, v3
	v_max_f32_e32 v4, 0xc1f00000, v4
	v_max_f32_e32 v159, 0xc1f00000, v159
	v_max_f32_e32 v190, 0xc1f00000, v190
	v_max_f32_e32 v191, 0xc1f00000, v191
	v_max_f32_e32 v203, 0xc1f00000, v203
	v_max_f32_e32 v204, 0xc1f00000, v204
	v_max_f32_e32 v205, 0xc1f00000, v205
	v_mul_f32_e32 v3, 0xbfb8aa3b, v3
	v_mul_f32_e32 v4, 0xbfb8aa3b, v4
	v_mul_f32_e32 v159, 0xbfb8aa3b, v159
	v_mul_f32_e32 v190, 0xbfb8aa3b, v190
	v_mul_f32_e32 v191, 0xbfb8aa3b, v191
	v_mul_f32_e32 v203, 0xbfb8aa3b, v203
	v_mul_f32_e32 v204, 0xbfb8aa3b, v204
	v_mul_f32_e32 v205, 0xbfb8aa3b, v205
	v_exp_f32_e32 v3, v3
	v_exp_f32_e32 v4, v4
	v_exp_f32_e32 v159, v159
	v_exp_f32_e32 v190, v190
	v_exp_f32_e32 v191, v191
	v_exp_f32_e32 v203, v203
	v_exp_f32_e32 v204, v204
	v_exp_f32_e32 v205, v205
	v_add_f32_e32 v3, 1.0, v3
	v_add_f32_e32 v4, 1.0, v4
	v_add_f32_e32 v159, 1.0, v159
	v_add_f32_e32 v190, 1.0, v190
	v_add_f32_e32 v191, 1.0, v191
	v_add_f32_e32 v203, 1.0, v203
	v_add_f32_e32 v204, 1.0, v204
	v_add_f32_e32 v205, 1.0, v205
	v_rcp_f32_e32 v3, v3
	v_rcp_f32_e32 v4, v4
	v_rcp_f32_e32 v159, v159
	v_rcp_f32_e32 v190, v190
	v_rcp_f32_e32 v191, v191
	v_rcp_f32_e32 v203, v203
	v_rcp_f32_e32 v204, v204
	v_rcp_f32_e32 v205, v205
	v_mul_f32_e32 v3, v98, v3
	v_mul_f32_e32 v4, v99, v4
	v_mul_f32_e32 v159, v100, v159
	v_mul_f32_e32 v190, v101, v190
	v_mul_f32_e32 v191, v94, v191
	v_mul_f32_e32 v203, v95, v203
	v_mul_f32_e32 v204, v96, v204
	v_mul_f32_e32 v205, v97, v205
	v_cvt_pk_bf16_f32 v138, v3, v4
	v_cvt_pk_bf16_f32 v139, v159, v190
	v_cvt_pk_bf16_f32 v140, v191, v203
	v_cvt_pk_bf16_f32 v141, v204, v205
	s_add_u32 s32, s44, 0x100
	s_addc_u32 s33, s45, 0
	global_store_dwordx4 v252, v[138:141], s[32:33]
	s_waitcnt vmcnt(15)
	v_lshlrev_b32_e32 v3, 16, v142
	v_and_b32_e32 v4, s74, v142
	v_lshlrev_b32_e32 v159, 16, v143
	v_and_b32_e32 v190, s74, v143
	v_lshlrev_b32_e32 v191, 16, v144
	v_and_b32_e32 v203, s74, v144
	v_lshlrev_b32_e32 v204, 16, v145
	v_and_b32_e32 v205, s74, v145
	v_max_f32_e32 v3, v3, v3
	v_max_f32_e32 v4, v4, v4
	v_max_f32_e32 v159, v159, v159
	v_max_f32_e32 v190, v190, v190
	v_max_f32_e32 v191, v191, v191
	v_max_f32_e32 v203, v203, v203
	v_max_f32_e32 v204, v204, v204
	v_max_f32_e32 v205, v205, v205
	v_max_f32_e32 v3, 0xc1f00000, v3
	v_max_f32_e32 v4, 0xc1f00000, v4
	v_max_f32_e32 v159, 0xc1f00000, v159
	v_max_f32_e32 v190, 0xc1f00000, v190
	v_max_f32_e32 v191, 0xc1f00000, v191
	v_max_f32_e32 v203, 0xc1f00000, v203
	v_max_f32_e32 v204, 0xc1f00000, v204
	v_max_f32_e32 v205, 0xc1f00000, v205
	v_mul_f32_e32 v3, 0xbfb8aa3b, v3
	v_mul_f32_e32 v4, 0xbfb8aa3b, v4
	v_mul_f32_e32 v159, 0xbfb8aa3b, v159
	v_mul_f32_e32 v190, 0xbfb8aa3b, v190
	v_mul_f32_e32 v191, 0xbfb8aa3b, v191
	v_mul_f32_e32 v203, 0xbfb8aa3b, v203
	v_mul_f32_e32 v204, 0xbfb8aa3b, v204
	v_mul_f32_e32 v205, 0xbfb8aa3b, v205
	v_exp_f32_e32 v3, v3
	v_exp_f32_e32 v4, v4
	v_exp_f32_e32 v159, v159
	v_exp_f32_e32 v190, v190
	v_exp_f32_e32 v191, v191
	v_exp_f32_e32 v203, v203
	v_exp_f32_e32 v204, v204
	v_exp_f32_e32 v205, v205
	v_add_f32_e32 v3, 1.0, v3
	v_add_f32_e32 v4, 1.0, v4
	v_add_f32_e32 v159, 1.0, v159
	v_add_f32_e32 v190, 1.0, v190
	v_add_f32_e32 v191, 1.0, v191
	v_add_f32_e32 v203, 1.0, v203
	v_add_f32_e32 v204, 1.0, v204
	v_add_f32_e32 v205, 1.0, v205
	v_rcp_f32_e32 v3, v3
	v_rcp_f32_e32 v4, v4
	v_rcp_f32_e32 v159, v159
	v_rcp_f32_e32 v190, v190
	v_rcp_f32_e32 v191, v191
	v_rcp_f32_e32 v203, v203
	v_rcp_f32_e32 v204, v204
	v_rcp_f32_e32 v205, v205
	v_mul_f32_e32 v3, v122, v3
	v_mul_f32_e32 v4, v123, v4
	v_mul_f32_e32 v159, v124, v159
	v_mul_f32_e32 v190, v125, v190
	v_mul_f32_e32 v191, v118, v191
	v_mul_f32_e32 v203, v119, v203
	v_mul_f32_e32 v204, v120, v204
	v_mul_f32_e32 v205, v121, v205
	v_cvt_pk_bf16_f32 v142, v3, v4
	v_cvt_pk_bf16_f32 v143, v159, v190
	v_cvt_pk_bf16_f32 v144, v191, v203
	v_cvt_pk_bf16_f32 v145, v204, v205
	s_add_u32 s32, s44, 0x10000
	s_addc_u32 s33, s45, 0
	global_store_dwordx4 v252, v[142:145], s[32:33]
	s_waitcnt vmcnt(15)
	v_lshlrev_b32_e32 v3, 16, v146
	v_and_b32_e32 v4, s74, v146
	v_lshlrev_b32_e32 v159, 16, v147
	v_and_b32_e32 v190, s74, v147
	v_lshlrev_b32_e32 v191, 16, v148
	v_and_b32_e32 v203, s74, v148
	v_lshlrev_b32_e32 v204, 16, v149
	v_and_b32_e32 v205, s74, v149
	v_max_f32_e32 v3, v3, v3
	v_max_f32_e32 v4, v4, v4
	v_max_f32_e32 v159, v159, v159
	v_max_f32_e32 v190, v190, v190
	v_max_f32_e32 v191, v191, v191
	v_max_f32_e32 v203, v203, v203
	v_max_f32_e32 v204, v204, v204
	v_max_f32_e32 v205, v205, v205
	v_max_f32_e32 v3, 0xc1f00000, v3
	v_max_f32_e32 v4, 0xc1f00000, v4
	v_max_f32_e32 v159, 0xc1f00000, v159
	v_max_f32_e32 v190, 0xc1f00000, v190
	v_max_f32_e32 v191, 0xc1f00000, v191
	v_max_f32_e32 v203, 0xc1f00000, v203
	v_max_f32_e32 v204, 0xc1f00000, v204
	v_max_f32_e32 v205, 0xc1f00000, v205
	v_mul_f32_e32 v3, 0xbfb8aa3b, v3
	v_mul_f32_e32 v4, 0xbfb8aa3b, v4
	v_mul_f32_e32 v159, 0xbfb8aa3b, v159
	v_mul_f32_e32 v190, 0xbfb8aa3b, v190
	v_mul_f32_e32 v191, 0xbfb8aa3b, v191
	v_mul_f32_e32 v203, 0xbfb8aa3b, v203
	v_mul_f32_e32 v204, 0xbfb8aa3b, v204
	v_mul_f32_e32 v205, 0xbfb8aa3b, v205
	v_exp_f32_e32 v3, v3
	v_exp_f32_e32 v4, v4
	v_exp_f32_e32 v159, v159
	v_exp_f32_e32 v190, v190
	v_exp_f32_e32 v191, v191
	v_exp_f32_e32 v203, v203
	v_exp_f32_e32 v204, v204
	v_exp_f32_e32 v205, v205
	v_add_f32_e32 v3, 1.0, v3
	v_add_f32_e32 v4, 1.0, v4
	v_add_f32_e32 v159, 1.0, v159
	v_add_f32_e32 v190, 1.0, v190
	v_add_f32_e32 v191, 1.0, v191
	v_add_f32_e32 v203, 1.0, v203
	v_add_f32_e32 v204, 1.0, v204
	v_add_f32_e32 v205, 1.0, v205
	v_rcp_f32_e32 v3, v3
	v_rcp_f32_e32 v4, v4
	v_rcp_f32_e32 v159, v159
	v_rcp_f32_e32 v190, v190
	v_rcp_f32_e32 v191, v191
	v_rcp_f32_e32 v203, v203
	v_rcp_f32_e32 v204, v204
	v_rcp_f32_e32 v205, v205
	v_mul_f32_e32 v3, v90, v3
	v_mul_f32_e32 v4, v91, v4
	v_mul_f32_e32 v159, v92, v159
	v_mul_f32_e32 v190, v93, v190
	v_mul_f32_e32 v191, v86, v191
	v_mul_f32_e32 v203, v87, v203
	v_mul_f32_e32 v204, v88, v204
	v_mul_f32_e32 v205, v89, v205
	v_cvt_pk_bf16_f32 v146, v3, v4
	v_cvt_pk_bf16_f32 v147, v159, v190
	v_cvt_pk_bf16_f32 v148, v191, v203
	v_cvt_pk_bf16_f32 v149, v204, v205
	s_add_u32 s32, s44, 0x10100
	s_addc_u32 s33, s45, 0
	global_store_dwordx4 v252, v[146:149], s[32:33]
	s_waitcnt vmcnt(15)
	v_lshlrev_b32_e32 v3, 16, v180
	v_and_b32_e32 v4, s74, v180
	v_lshlrev_b32_e32 v159, 16, v181
	v_and_b32_e32 v190, s74, v181
	v_lshlrev_b32_e32 v191, 16, v182
	v_and_b32_e32 v203, s74, v182
	v_lshlrev_b32_e32 v204, 16, v183
	v_and_b32_e32 v205, s74, v183
	v_max_f32_e32 v3, v3, v3
	v_max_f32_e32 v4, v4, v4
	v_max_f32_e32 v159, v159, v159
	v_max_f32_e32 v190, v190, v190
	v_max_f32_e32 v191, v191, v191
	v_max_f32_e32 v203, v203, v203
	v_max_f32_e32 v204, v204, v204
	v_max_f32_e32 v205, v205, v205
	v_max_f32_e32 v3, 0xc1f00000, v3
	v_max_f32_e32 v4, 0xc1f00000, v4
	v_max_f32_e32 v159, 0xc1f00000, v159
	v_max_f32_e32 v190, 0xc1f00000, v190
	v_max_f32_e32 v191, 0xc1f00000, v191
	v_max_f32_e32 v203, 0xc1f00000, v203
	v_max_f32_e32 v204, 0xc1f00000, v204
	v_max_f32_e32 v205, 0xc1f00000, v205
	v_mul_f32_e32 v3, 0xbfb8aa3b, v3
	v_mul_f32_e32 v4, 0xbfb8aa3b, v4
	v_mul_f32_e32 v159, 0xbfb8aa3b, v159
	v_mul_f32_e32 v190, 0xbfb8aa3b, v190
	v_mul_f32_e32 v191, 0xbfb8aa3b, v191
	v_mul_f32_e32 v203, 0xbfb8aa3b, v203
	v_mul_f32_e32 v204, 0xbfb8aa3b, v204
	v_mul_f32_e32 v205, 0xbfb8aa3b, v205
	v_exp_f32_e32 v3, v3
	v_exp_f32_e32 v4, v4
	v_exp_f32_e32 v159, v159
	v_exp_f32_e32 v190, v190
	v_exp_f32_e32 v191, v191
	v_exp_f32_e32 v203, v203
	v_exp_f32_e32 v204, v204
	v_exp_f32_e32 v205, v205
	v_add_f32_e32 v3, 1.0, v3
	v_add_f32_e32 v4, 1.0, v4
	v_add_f32_e32 v159, 1.0, v159
	v_add_f32_e32 v190, 1.0, v190
	v_add_f32_e32 v191, 1.0, v191
	v_add_f32_e32 v203, 1.0, v203
	v_add_f32_e32 v204, 1.0, v204
	v_add_f32_e32 v205, 1.0, v205
	v_rcp_f32_e32 v3, v3
	v_rcp_f32_e32 v4, v4
	v_rcp_f32_e32 v159, v159
	v_rcp_f32_e32 v190, v190
	v_rcp_f32_e32 v191, v191
	v_rcp_f32_e32 v203, v203
	v_rcp_f32_e32 v204, v204
	v_rcp_f32_e32 v205, v205
	v_mul_f32_e32 v3, v114, v3
	v_mul_f32_e32 v4, v115, v4
	v_mul_f32_e32 v159, v116, v159
	v_mul_f32_e32 v190, v117, v190
	v_mul_f32_e32 v191, v110, v191
	v_mul_f32_e32 v203, v111, v203
	v_mul_f32_e32 v204, v112, v204
	v_mul_f32_e32 v205, v113, v205
	v_cvt_pk_bf16_f32 v180, v3, v4
	v_cvt_pk_bf16_f32 v181, v159, v190
	v_cvt_pk_bf16_f32 v182, v191, v203
	v_cvt_pk_bf16_f32 v183, v204, v205
	s_add_u32 s32, s44, 0x20000
	s_addc_u32 s33, s45, 0
	global_store_dwordx4 v252, v[180:183], s[32:33]
	s_waitcnt vmcnt(15)
	v_lshlrev_b32_e32 v3, 16, v186
	v_and_b32_e32 v4, s74, v186
	v_lshlrev_b32_e32 v159, 16, v187
	v_and_b32_e32 v190, s74, v187
	v_lshlrev_b32_e32 v191, 16, v188
	v_and_b32_e32 v203, s74, v188
	v_lshlrev_b32_e32 v204, 16, v189
	v_and_b32_e32 v205, s74, v189
	v_max_f32_e32 v3, v3, v3
	v_max_f32_e32 v4, v4, v4
	v_max_f32_e32 v159, v159, v159
	v_max_f32_e32 v190, v190, v190
	v_max_f32_e32 v191, v191, v191
	v_max_f32_e32 v203, v203, v203
	v_max_f32_e32 v204, v204, v204
	v_max_f32_e32 v205, v205, v205
	v_max_f32_e32 v3, 0xc1f00000, v3
	v_max_f32_e32 v4, 0xc1f00000, v4
	v_max_f32_e32 v159, 0xc1f00000, v159
	v_max_f32_e32 v190, 0xc1f00000, v190
	v_max_f32_e32 v191, 0xc1f00000, v191
	v_max_f32_e32 v203, 0xc1f00000, v203
	v_max_f32_e32 v204, 0xc1f00000, v204
	v_max_f32_e32 v205, 0xc1f00000, v205
	v_mul_f32_e32 v3, 0xbfb8aa3b, v3
	v_mul_f32_e32 v4, 0xbfb8aa3b, v4
	v_mul_f32_e32 v159, 0xbfb8aa3b, v159
	v_mul_f32_e32 v190, 0xbfb8aa3b, v190
	v_mul_f32_e32 v191, 0xbfb8aa3b, v191
	v_mul_f32_e32 v203, 0xbfb8aa3b, v203
	v_mul_f32_e32 v204, 0xbfb8aa3b, v204
	v_mul_f32_e32 v205, 0xbfb8aa3b, v205
	v_exp_f32_e32 v3, v3
	v_exp_f32_e32 v4, v4
	v_exp_f32_e32 v159, v159
	v_exp_f32_e32 v190, v190
	v_exp_f32_e32 v191, v191
	v_exp_f32_e32 v203, v203
	v_exp_f32_e32 v204, v204
	v_exp_f32_e32 v205, v205
	v_add_f32_e32 v3, 1.0, v3
	v_add_f32_e32 v4, 1.0, v4
	v_add_f32_e32 v159, 1.0, v159
	v_add_f32_e32 v190, 1.0, v190
	v_add_f32_e32 v191, 1.0, v191
	v_add_f32_e32 v203, 1.0, v203
	v_add_f32_e32 v204, 1.0, v204
	v_add_f32_e32 v205, 1.0, v205
	v_rcp_f32_e32 v3, v3
	v_rcp_f32_e32 v4, v4
	v_rcp_f32_e32 v159, v159
	v_rcp_f32_e32 v190, v190
	v_rcp_f32_e32 v191, v191
	v_rcp_f32_e32 v203, v203
	v_rcp_f32_e32 v204, v204
	v_rcp_f32_e32 v205, v205
	v_mul_f32_e32 v3, v82, v3
	v_mul_f32_e32 v4, v83, v4
	v_mul_f32_e32 v159, v84, v159
	v_mul_f32_e32 v190, v85, v190
	v_mul_f32_e32 v191, v78, v191
	v_mul_f32_e32 v203, v79, v203
	v_mul_f32_e32 v204, v80, v204
	v_mul_f32_e32 v205, v81, v205
	v_cvt_pk_bf16_f32 v186, v3, v4
	v_cvt_pk_bf16_f32 v187, v159, v190
	v_cvt_pk_bf16_f32 v188, v191, v203
	v_cvt_pk_bf16_f32 v189, v204, v205
	s_add_u32 s32, s44, 0x20100
	s_addc_u32 s33, s45, 0
	global_store_dwordx4 v252, v[186:189], s[32:33]
	s_waitcnt vmcnt(15)
	v_lshlrev_b32_e32 v3, 16, v212
	v_and_b32_e32 v4, s74, v212
	v_lshlrev_b32_e32 v159, 16, v213
	v_and_b32_e32 v190, s74, v213
	v_lshlrev_b32_e32 v191, 16, v214
	v_and_b32_e32 v203, s74, v214
	v_lshlrev_b32_e32 v204, 16, v215
	v_and_b32_e32 v205, s74, v215
	v_max_f32_e32 v3, v3, v3
	v_max_f32_e32 v4, v4, v4
	v_max_f32_e32 v159, v159, v159
	v_max_f32_e32 v190, v190, v190
	v_max_f32_e32 v191, v191, v191
	v_max_f32_e32 v203, v203, v203
	v_max_f32_e32 v204, v204, v204
	v_max_f32_e32 v205, v205, v205
	v_max_f32_e32 v3, 0xc1f00000, v3
	v_max_f32_e32 v4, 0xc1f00000, v4
	v_max_f32_e32 v159, 0xc1f00000, v159
	v_max_f32_e32 v190, 0xc1f00000, v190
	v_max_f32_e32 v191, 0xc1f00000, v191
	v_max_f32_e32 v203, 0xc1f00000, v203
	v_max_f32_e32 v204, 0xc1f00000, v204
	v_max_f32_e32 v205, 0xc1f00000, v205
	v_mul_f32_e32 v3, 0xbfb8aa3b, v3
	v_mul_f32_e32 v4, 0xbfb8aa3b, v4
	v_mul_f32_e32 v159, 0xbfb8aa3b, v159
	v_mul_f32_e32 v190, 0xbfb8aa3b, v190
	v_mul_f32_e32 v191, 0xbfb8aa3b, v191
	v_mul_f32_e32 v203, 0xbfb8aa3b, v203
	v_mul_f32_e32 v204, 0xbfb8aa3b, v204
	v_mul_f32_e32 v205, 0xbfb8aa3b, v205
	v_exp_f32_e32 v3, v3
	v_exp_f32_e32 v4, v4
	v_exp_f32_e32 v159, v159
	v_exp_f32_e32 v190, v190
	v_exp_f32_e32 v191, v191
	v_exp_f32_e32 v203, v203
	v_exp_f32_e32 v204, v204
	v_exp_f32_e32 v205, v205
	v_add_f32_e32 v3, 1.0, v3
	v_add_f32_e32 v4, 1.0, v4
	v_add_f32_e32 v159, 1.0, v159
	v_add_f32_e32 v190, 1.0, v190
	v_add_f32_e32 v191, 1.0, v191
	v_add_f32_e32 v203, 1.0, v203
	v_add_f32_e32 v204, 1.0, v204
	v_add_f32_e32 v205, 1.0, v205
	v_rcp_f32_e32 v3, v3
	v_rcp_f32_e32 v4, v4
	v_rcp_f32_e32 v159, v159
	v_rcp_f32_e32 v190, v190
	v_rcp_f32_e32 v191, v191
	v_rcp_f32_e32 v203, v203
	v_rcp_f32_e32 v204, v204
	v_rcp_f32_e32 v205, v205
	v_mul_f32_e32 v3, v106, v3
	v_mul_f32_e32 v4, v107, v4
	v_mul_f32_e32 v159, v108, v159
	v_mul_f32_e32 v190, v109, v190
	v_mul_f32_e32 v191, v102, v191
	v_mul_f32_e32 v203, v103, v203
	v_mul_f32_e32 v204, v104, v204
	v_mul_f32_e32 v205, v105, v205
	v_cvt_pk_bf16_f32 v212, v3, v4
	v_cvt_pk_bf16_f32 v213, v159, v190
	v_cvt_pk_bf16_f32 v214, v191, v203
	v_cvt_pk_bf16_f32 v215, v204, v205
	s_add_u32 s32, s44, 0x30000
	s_addc_u32 s33, s45, 0
	global_store_dwordx4 v252, v[212:215], s[32:33]
	s_waitcnt vmcnt(15)
	v_lshlrev_b32_e32 v3, 16, v216
	v_and_b32_e32 v4, s74, v216
	v_lshlrev_b32_e32 v159, 16, v217
	v_and_b32_e32 v190, s74, v217
	v_lshlrev_b32_e32 v191, 16, v218
	v_and_b32_e32 v203, s74, v218
	v_lshlrev_b32_e32 v204, 16, v219
	v_and_b32_e32 v205, s74, v219
	v_max_f32_e32 v3, v3, v3
	v_max_f32_e32 v4, v4, v4
	v_max_f32_e32 v159, v159, v159
	v_max_f32_e32 v190, v190, v190
	v_max_f32_e32 v191, v191, v191
	v_max_f32_e32 v203, v203, v203
	v_max_f32_e32 v204, v204, v204
	v_max_f32_e32 v205, v205, v205
	v_max_f32_e32 v3, 0xc1f00000, v3
	v_max_f32_e32 v4, 0xc1f00000, v4
	v_max_f32_e32 v159, 0xc1f00000, v159
	v_max_f32_e32 v190, 0xc1f00000, v190
	v_max_f32_e32 v191, 0xc1f00000, v191
	v_max_f32_e32 v203, 0xc1f00000, v203
	v_max_f32_e32 v204, 0xc1f00000, v204
	v_max_f32_e32 v205, 0xc1f00000, v205
	v_mul_f32_e32 v3, 0xbfb8aa3b, v3
	v_mul_f32_e32 v4, 0xbfb8aa3b, v4
	v_mul_f32_e32 v159, 0xbfb8aa3b, v159
	v_mul_f32_e32 v190, 0xbfb8aa3b, v190
	v_mul_f32_e32 v191, 0xbfb8aa3b, v191
	v_mul_f32_e32 v203, 0xbfb8aa3b, v203
	v_mul_f32_e32 v204, 0xbfb8aa3b, v204
	v_mul_f32_e32 v205, 0xbfb8aa3b, v205
	v_exp_f32_e32 v3, v3
	v_exp_f32_e32 v4, v4
	v_exp_f32_e32 v159, v159
	v_exp_f32_e32 v190, v190
	v_exp_f32_e32 v191, v191
	v_exp_f32_e32 v203, v203
	v_exp_f32_e32 v204, v204
	v_exp_f32_e32 v205, v205
	v_add_f32_e32 v3, 1.0, v3
	v_add_f32_e32 v4, 1.0, v4
	v_add_f32_e32 v159, 1.0, v159
	v_add_f32_e32 v190, 1.0, v190
	v_add_f32_e32 v191, 1.0, v191
	v_add_f32_e32 v203, 1.0, v203
	v_add_f32_e32 v204, 1.0, v204
	v_add_f32_e32 v205, 1.0, v205
	v_rcp_f32_e32 v3, v3
	v_rcp_f32_e32 v4, v4
	v_rcp_f32_e32 v159, v159
	v_rcp_f32_e32 v190, v190
	v_rcp_f32_e32 v191, v191
	v_rcp_f32_e32 v203, v203
	v_rcp_f32_e32 v204, v204
	v_rcp_f32_e32 v205, v205
	v_mul_f32_e32 v3, v74, v3
	v_mul_f32_e32 v4, v75, v4
	v_mul_f32_e32 v159, v76, v159
	v_mul_f32_e32 v190, v77, v190
	v_mul_f32_e32 v191, v70, v191
	v_mul_f32_e32 v203, v71, v203
	v_mul_f32_e32 v204, v72, v204
	v_mul_f32_e32 v205, v73, v205
	v_cvt_pk_bf16_f32 v216, v3, v4
	v_cvt_pk_bf16_f32 v217, v159, v190
	v_cvt_pk_bf16_f32 v218, v191, v203
	v_cvt_pk_bf16_f32 v219, v204, v205
	s_add_u32 s32, s44, 0x30100
	s_addc_u32 s33, s45, 0
	global_store_dwordx4 v252, v[216:219], s[32:33]
	s_waitcnt vmcnt(15)
	v_lshlrev_b32_e32 v3, 16, v220
	v_and_b32_e32 v4, s74, v220
	v_lshlrev_b32_e32 v159, 16, v221
	v_and_b32_e32 v190, s74, v221
	v_lshlrev_b32_e32 v191, 16, v222
	v_and_b32_e32 v203, s74, v222
	v_lshlrev_b32_e32 v204, 16, v223
	v_and_b32_e32 v205, s74, v223
	v_max_f32_e32 v3, v3, v3
	v_max_f32_e32 v4, v4, v4
	v_max_f32_e32 v159, v159, v159
	v_max_f32_e32 v190, v190, v190
	v_max_f32_e32 v191, v191, v191
	v_max_f32_e32 v203, v203, v203
	v_max_f32_e32 v204, v204, v204
	v_max_f32_e32 v205, v205, v205
	v_max_f32_e32 v3, 0xc1f00000, v3
	v_max_f32_e32 v4, 0xc1f00000, v4
	v_max_f32_e32 v159, 0xc1f00000, v159
	v_max_f32_e32 v190, 0xc1f00000, v190
	v_max_f32_e32 v191, 0xc1f00000, v191
	v_max_f32_e32 v203, 0xc1f00000, v203
	v_max_f32_e32 v204, 0xc1f00000, v204
	v_max_f32_e32 v205, 0xc1f00000, v205
	v_mul_f32_e32 v3, 0xbfb8aa3b, v3
	v_mul_f32_e32 v4, 0xbfb8aa3b, v4
	v_mul_f32_e32 v159, 0xbfb8aa3b, v159
	v_mul_f32_e32 v190, 0xbfb8aa3b, v190
	v_mul_f32_e32 v191, 0xbfb8aa3b, v191
	v_mul_f32_e32 v203, 0xbfb8aa3b, v203
	v_mul_f32_e32 v204, 0xbfb8aa3b, v204
	v_mul_f32_e32 v205, 0xbfb8aa3b, v205
	v_exp_f32_e32 v3, v3
	v_exp_f32_e32 v4, v4
	v_exp_f32_e32 v159, v159
	v_exp_f32_e32 v190, v190
	v_exp_f32_e32 v191, v191
	v_exp_f32_e32 v203, v203
	v_exp_f32_e32 v204, v204
	v_exp_f32_e32 v205, v205
	v_add_f32_e32 v3, 1.0, v3
	v_add_f32_e32 v4, 1.0, v4
	v_add_f32_e32 v159, 1.0, v159
	v_add_f32_e32 v190, 1.0, v190
	v_add_f32_e32 v191, 1.0, v191
	v_add_f32_e32 v203, 1.0, v203
	v_add_f32_e32 v204, 1.0, v204
	v_add_f32_e32 v205, 1.0, v205
	v_rcp_f32_e32 v3, v3
	v_rcp_f32_e32 v4, v4
	v_rcp_f32_e32 v159, v159
	v_rcp_f32_e32 v190, v190
	v_rcp_f32_e32 v191, v191
	v_rcp_f32_e32 v203, v203
	v_rcp_f32_e32 v204, v204
	v_rcp_f32_e32 v205, v205
	v_mul_f32_e32 v3, v66, v3
	v_mul_f32_e32 v4, v67, v4
	v_mul_f32_e32 v159, v68, v159
	v_mul_f32_e32 v190, v69, v190
	v_mul_f32_e32 v191, v62, v191
	v_mul_f32_e32 v203, v63, v203
	v_mul_f32_e32 v204, v64, v204
	v_mul_f32_e32 v205, v65, v205
	v_cvt_pk_bf16_f32 v220, v3, v4
	v_cvt_pk_bf16_f32 v221, v159, v190
	v_cvt_pk_bf16_f32 v222, v191, v203
	v_cvt_pk_bf16_f32 v223, v204, v205
	s_add_u32 s32, s44, 0x80000
	s_addc_u32 s33, s45, 0
	global_store_dwordx4 v252, v[220:223], s[32:33]
	s_waitcnt vmcnt(15)
	v_lshlrev_b32_e32 v3, 16, v224
	v_and_b32_e32 v4, s74, v224
	v_lshlrev_b32_e32 v159, 16, v225
	v_and_b32_e32 v190, s74, v225
	v_lshlrev_b32_e32 v191, 16, v226
	v_and_b32_e32 v203, s74, v226
	v_lshlrev_b32_e32 v204, 16, v227
	v_and_b32_e32 v205, s74, v227
	v_max_f32_e32 v3, v3, v3
	v_max_f32_e32 v4, v4, v4
	v_max_f32_e32 v159, v159, v159
	v_max_f32_e32 v190, v190, v190
	v_max_f32_e32 v191, v191, v191
	v_max_f32_e32 v203, v203, v203
	v_max_f32_e32 v204, v204, v204
	v_max_f32_e32 v205, v205, v205
	v_max_f32_e32 v3, 0xc1f00000, v3
	v_max_f32_e32 v4, 0xc1f00000, v4
	v_max_f32_e32 v159, 0xc1f00000, v159
	v_max_f32_e32 v190, 0xc1f00000, v190
	v_max_f32_e32 v191, 0xc1f00000, v191
	v_max_f32_e32 v203, 0xc1f00000, v203
	v_max_f32_e32 v204, 0xc1f00000, v204
	v_max_f32_e32 v205, 0xc1f00000, v205
	v_mul_f32_e32 v3, 0xbfb8aa3b, v3
	v_mul_f32_e32 v4, 0xbfb8aa3b, v4
	v_mul_f32_e32 v159, 0xbfb8aa3b, v159
	v_mul_f32_e32 v190, 0xbfb8aa3b, v190
	v_mul_f32_e32 v191, 0xbfb8aa3b, v191
	v_mul_f32_e32 v203, 0xbfb8aa3b, v203
	v_mul_f32_e32 v204, 0xbfb8aa3b, v204
	v_mul_f32_e32 v205, 0xbfb8aa3b, v205
	v_exp_f32_e32 v3, v3
	v_exp_f32_e32 v4, v4
	v_exp_f32_e32 v159, v159
	v_exp_f32_e32 v190, v190
	v_exp_f32_e32 v191, v191
	v_exp_f32_e32 v203, v203
	v_exp_f32_e32 v204, v204
	v_exp_f32_e32 v205, v205
	v_add_f32_e32 v3, 1.0, v3
	v_add_f32_e32 v4, 1.0, v4
	v_add_f32_e32 v159, 1.0, v159
	v_add_f32_e32 v190, 1.0, v190
	v_add_f32_e32 v191, 1.0, v191
	v_add_f32_e32 v203, 1.0, v203
	v_add_f32_e32 v204, 1.0, v204
	v_add_f32_e32 v205, 1.0, v205
	v_rcp_f32_e32 v3, v3
	v_rcp_f32_e32 v4, v4
	v_rcp_f32_e32 v159, v159
	v_rcp_f32_e32 v190, v190
	v_rcp_f32_e32 v191, v191
	v_rcp_f32_e32 v203, v203
	v_rcp_f32_e32 v204, v204
	v_rcp_f32_e32 v205, v205
	v_mul_f32_e32 v3, v34, v3
	v_mul_f32_e32 v4, v35, v4
	v_mul_f32_e32 v159, v36, v159
	v_mul_f32_e32 v190, v37, v190
	v_mul_f32_e32 v191, v30, v191
	v_mul_f32_e32 v203, v31, v203
	v_mul_f32_e32 v204, v32, v204
	v_mul_f32_e32 v205, v33, v205
	v_cvt_pk_bf16_f32 v224, v3, v4
	v_cvt_pk_bf16_f32 v225, v159, v190
	v_cvt_pk_bf16_f32 v226, v191, v203
	v_cvt_pk_bf16_f32 v227, v204, v205
	s_add_u32 s32, s44, 0x80100
	s_addc_u32 s33, s45, 0
	global_store_dwordx4 v252, v[224:227], s[32:33]
	s_waitcnt vmcnt(15)
	v_lshlrev_b32_e32 v3, 16, v228
	v_and_b32_e32 v4, s74, v228
	v_lshlrev_b32_e32 v159, 16, v229
	v_and_b32_e32 v190, s74, v229
	v_lshlrev_b32_e32 v191, 16, v230
	v_and_b32_e32 v203, s74, v230
	v_lshlrev_b32_e32 v204, 16, v231
	v_and_b32_e32 v205, s74, v231
	v_max_f32_e32 v3, v3, v3
	v_max_f32_e32 v4, v4, v4
	v_max_f32_e32 v159, v159, v159
	v_max_f32_e32 v190, v190, v190
	v_max_f32_e32 v191, v191, v191
	v_max_f32_e32 v203, v203, v203
	v_max_f32_e32 v204, v204, v204
	v_max_f32_e32 v205, v205, v205
	v_max_f32_e32 v3, 0xc1f00000, v3
	v_max_f32_e32 v4, 0xc1f00000, v4
	v_max_f32_e32 v159, 0xc1f00000, v159
	v_max_f32_e32 v190, 0xc1f00000, v190
	v_max_f32_e32 v191, 0xc1f00000, v191
	v_max_f32_e32 v203, 0xc1f00000, v203
	v_max_f32_e32 v204, 0xc1f00000, v204
	v_max_f32_e32 v205, 0xc1f00000, v205
	v_mul_f32_e32 v3, 0xbfb8aa3b, v3
	v_mul_f32_e32 v4, 0xbfb8aa3b, v4
	v_mul_f32_e32 v159, 0xbfb8aa3b, v159
	v_mul_f32_e32 v190, 0xbfb8aa3b, v190
	v_mul_f32_e32 v191, 0xbfb8aa3b, v191
	v_mul_f32_e32 v203, 0xbfb8aa3b, v203
	v_mul_f32_e32 v204, 0xbfb8aa3b, v204
	v_mul_f32_e32 v205, 0xbfb8aa3b, v205
	v_exp_f32_e32 v3, v3
	v_exp_f32_e32 v4, v4
	v_exp_f32_e32 v159, v159
	v_exp_f32_e32 v190, v190
	v_exp_f32_e32 v191, v191
	v_exp_f32_e32 v203, v203
	v_exp_f32_e32 v204, v204
	v_exp_f32_e32 v205, v205
	v_add_f32_e32 v3, 1.0, v3
	v_add_f32_e32 v4, 1.0, v4
	v_add_f32_e32 v159, 1.0, v159
	v_add_f32_e32 v190, 1.0, v190
	v_add_f32_e32 v191, 1.0, v191
	v_add_f32_e32 v203, 1.0, v203
	v_add_f32_e32 v204, 1.0, v204
	v_add_f32_e32 v205, 1.0, v205
	v_rcp_f32_e32 v3, v3
	v_rcp_f32_e32 v4, v4
	v_rcp_f32_e32 v159, v159
	v_rcp_f32_e32 v190, v190
	v_rcp_f32_e32 v191, v191
	v_rcp_f32_e32 v203, v203
	v_rcp_f32_e32 v204, v204
	v_rcp_f32_e32 v205, v205
	v_mul_f32_e32 v3, v58, v3
	v_mul_f32_e32 v4, v59, v4
	v_mul_f32_e32 v159, v60, v159
	v_mul_f32_e32 v190, v61, v190
	v_mul_f32_e32 v191, v54, v191
	v_mul_f32_e32 v203, v55, v203
	v_mul_f32_e32 v204, v56, v204
	v_mul_f32_e32 v205, v57, v205
	v_cvt_pk_bf16_f32 v228, v3, v4
	v_cvt_pk_bf16_f32 v229, v159, v190
	v_cvt_pk_bf16_f32 v230, v191, v203
	v_cvt_pk_bf16_f32 v231, v204, v205
	s_add_u32 s32, s44, 0x90000
	s_addc_u32 s33, s45, 0
	global_store_dwordx4 v252, v[228:231], s[32:33]
	s_waitcnt vmcnt(15)
	v_lshlrev_b32_e32 v3, 16, v232
	v_and_b32_e32 v4, s74, v232
	v_lshlrev_b32_e32 v159, 16, v233
	v_and_b32_e32 v190, s74, v233
	v_lshlrev_b32_e32 v191, 16, v234
	v_and_b32_e32 v203, s74, v234
	v_lshlrev_b32_e32 v204, 16, v235
	v_and_b32_e32 v205, s74, v235
	v_max_f32_e32 v3, v3, v3
	v_max_f32_e32 v4, v4, v4
	v_max_f32_e32 v159, v159, v159
	v_max_f32_e32 v190, v190, v190
	v_max_f32_e32 v191, v191, v191
	v_max_f32_e32 v203, v203, v203
	v_max_f32_e32 v204, v204, v204
	v_max_f32_e32 v205, v205, v205
	v_max_f32_e32 v3, 0xc1f00000, v3
	v_max_f32_e32 v4, 0xc1f00000, v4
	v_max_f32_e32 v159, 0xc1f00000, v159
	v_max_f32_e32 v190, 0xc1f00000, v190
	v_max_f32_e32 v191, 0xc1f00000, v191
	v_max_f32_e32 v203, 0xc1f00000, v203
	v_max_f32_e32 v204, 0xc1f00000, v204
	v_max_f32_e32 v205, 0xc1f00000, v205
	v_mul_f32_e32 v3, 0xbfb8aa3b, v3
	v_mul_f32_e32 v4, 0xbfb8aa3b, v4
	v_mul_f32_e32 v159, 0xbfb8aa3b, v159
	v_mul_f32_e32 v190, 0xbfb8aa3b, v190
	v_mul_f32_e32 v191, 0xbfb8aa3b, v191
	v_mul_f32_e32 v203, 0xbfb8aa3b, v203
	v_mul_f32_e32 v204, 0xbfb8aa3b, v204
	v_mul_f32_e32 v205, 0xbfb8aa3b, v205
	v_exp_f32_e32 v3, v3
	v_exp_f32_e32 v4, v4
	v_exp_f32_e32 v159, v159
	v_exp_f32_e32 v190, v190
	v_exp_f32_e32 v191, v191
	v_exp_f32_e32 v203, v203
	v_exp_f32_e32 v204, v204
	v_exp_f32_e32 v205, v205
	v_add_f32_e32 v3, 1.0, v3
	v_add_f32_e32 v4, 1.0, v4
	v_add_f32_e32 v159, 1.0, v159
	v_add_f32_e32 v190, 1.0, v190
	v_add_f32_e32 v191, 1.0, v191
	v_add_f32_e32 v203, 1.0, v203
	v_add_f32_e32 v204, 1.0, v204
	v_add_f32_e32 v205, 1.0, v205
	v_rcp_f32_e32 v3, v3
	v_rcp_f32_e32 v4, v4
	v_rcp_f32_e32 v159, v159
	v_rcp_f32_e32 v190, v190
	v_rcp_f32_e32 v191, v191
	v_rcp_f32_e32 v203, v203
	v_rcp_f32_e32 v204, v204
	v_rcp_f32_e32 v205, v205
	v_mul_f32_e32 v3, v26, v3
	v_mul_f32_e32 v4, v27, v4
	v_mul_f32_e32 v159, v28, v159
	v_mul_f32_e32 v190, v29, v190
	v_mul_f32_e32 v191, v22, v191
	v_mul_f32_e32 v203, v23, v203
	v_mul_f32_e32 v204, v24, v204
	v_mul_f32_e32 v205, v25, v205
	v_cvt_pk_bf16_f32 v232, v3, v4
	v_cvt_pk_bf16_f32 v233, v159, v190
	v_cvt_pk_bf16_f32 v234, v191, v203
	v_cvt_pk_bf16_f32 v235, v204, v205
	s_add_u32 s32, s44, 0x90100
	s_addc_u32 s33, s45, 0
	global_store_dwordx4 v252, v[232:235], s[32:33]
	s_waitcnt vmcnt(15)
	v_lshlrev_b32_e32 v3, 16, v236
	v_and_b32_e32 v4, s74, v236
	v_lshlrev_b32_e32 v159, 16, v237
	v_and_b32_e32 v190, s74, v237
	v_lshlrev_b32_e32 v191, 16, v238
	v_and_b32_e32 v203, s74, v238
	v_lshlrev_b32_e32 v204, 16, v239
	v_and_b32_e32 v205, s74, v239
	v_max_f32_e32 v3, v3, v3
	v_max_f32_e32 v4, v4, v4
	v_max_f32_e32 v159, v159, v159
	v_max_f32_e32 v190, v190, v190
	v_max_f32_e32 v191, v191, v191
	v_max_f32_e32 v203, v203, v203
	v_max_f32_e32 v204, v204, v204
	v_max_f32_e32 v205, v205, v205
	v_max_f32_e32 v3, 0xc1f00000, v3
	v_max_f32_e32 v4, 0xc1f00000, v4
	v_max_f32_e32 v159, 0xc1f00000, v159
	v_max_f32_e32 v190, 0xc1f00000, v190
	v_max_f32_e32 v191, 0xc1f00000, v191
	v_max_f32_e32 v203, 0xc1f00000, v203
	v_max_f32_e32 v204, 0xc1f00000, v204
	v_max_f32_e32 v205, 0xc1f00000, v205
	v_mul_f32_e32 v3, 0xbfb8aa3b, v3
	v_mul_f32_e32 v4, 0xbfb8aa3b, v4
	v_mul_f32_e32 v159, 0xbfb8aa3b, v159
	v_mul_f32_e32 v190, 0xbfb8aa3b, v190
	v_mul_f32_e32 v191, 0xbfb8aa3b, v191
	v_mul_f32_e32 v203, 0xbfb8aa3b, v203
	v_mul_f32_e32 v204, 0xbfb8aa3b, v204
	v_mul_f32_e32 v205, 0xbfb8aa3b, v205
	v_exp_f32_e32 v3, v3
	v_exp_f32_e32 v4, v4
	v_exp_f32_e32 v159, v159
	v_exp_f32_e32 v190, v190
	v_exp_f32_e32 v191, v191
	v_exp_f32_e32 v203, v203
	v_exp_f32_e32 v204, v204
	v_exp_f32_e32 v205, v205
	v_add_f32_e32 v3, 1.0, v3
	v_add_f32_e32 v4, 1.0, v4
	v_add_f32_e32 v159, 1.0, v159
	v_add_f32_e32 v190, 1.0, v190
	v_add_f32_e32 v191, 1.0, v191
	v_add_f32_e32 v203, 1.0, v203
	v_add_f32_e32 v204, 1.0, v204
	v_add_f32_e32 v205, 1.0, v205
	v_rcp_f32_e32 v3, v3
	v_rcp_f32_e32 v4, v4
	v_rcp_f32_e32 v159, v159
	v_rcp_f32_e32 v190, v190
	v_rcp_f32_e32 v191, v191
	v_rcp_f32_e32 v203, v203
	v_rcp_f32_e32 v204, v204
	v_rcp_f32_e32 v205, v205
	v_mul_f32_e32 v3, v50, v3
	v_mul_f32_e32 v4, v51, v4
	v_mul_f32_e32 v159, v52, v159
	v_mul_f32_e32 v190, v53, v190
	v_mul_f32_e32 v191, v46, v191
	v_mul_f32_e32 v203, v47, v203
	v_mul_f32_e32 v204, v48, v204
	v_mul_f32_e32 v205, v49, v205
	v_cvt_pk_bf16_f32 v236, v3, v4
	v_cvt_pk_bf16_f32 v237, v159, v190
	v_cvt_pk_bf16_f32 v238, v191, v203
	v_cvt_pk_bf16_f32 v239, v204, v205
	s_add_u32 s32, s44, 0xa0000
	s_addc_u32 s33, s45, 0
	global_store_dwordx4 v252, v[236:239], s[32:33]
	s_waitcnt vmcnt(15)
	v_lshlrev_b32_e32 v3, 16, v240
	v_and_b32_e32 v4, s74, v240
	v_lshlrev_b32_e32 v159, 16, v241
	v_and_b32_e32 v190, s74, v241
	v_lshlrev_b32_e32 v191, 16, v242
	v_and_b32_e32 v203, s74, v242
	v_lshlrev_b32_e32 v204, 16, v243
	v_and_b32_e32 v205, s74, v243
	v_max_f32_e32 v3, v3, v3
	v_max_f32_e32 v4, v4, v4
	v_max_f32_e32 v159, v159, v159
	v_max_f32_e32 v190, v190, v190
	v_max_f32_e32 v191, v191, v191
	v_max_f32_e32 v203, v203, v203
	v_max_f32_e32 v204, v204, v204
	v_max_f32_e32 v205, v205, v205
	v_max_f32_e32 v3, 0xc1f00000, v3
	v_max_f32_e32 v4, 0xc1f00000, v4
	v_max_f32_e32 v159, 0xc1f00000, v159
	v_max_f32_e32 v190, 0xc1f00000, v190
	v_max_f32_e32 v191, 0xc1f00000, v191
	v_max_f32_e32 v203, 0xc1f00000, v203
	v_max_f32_e32 v204, 0xc1f00000, v204
	v_max_f32_e32 v205, 0xc1f00000, v205
	v_mul_f32_e32 v3, 0xbfb8aa3b, v3
	v_mul_f32_e32 v4, 0xbfb8aa3b, v4
	v_mul_f32_e32 v159, 0xbfb8aa3b, v159
	v_mul_f32_e32 v190, 0xbfb8aa3b, v190
	v_mul_f32_e32 v191, 0xbfb8aa3b, v191
	v_mul_f32_e32 v203, 0xbfb8aa3b, v203
	v_mul_f32_e32 v204, 0xbfb8aa3b, v204
	v_mul_f32_e32 v205, 0xbfb8aa3b, v205
	v_exp_f32_e32 v3, v3
	v_exp_f32_e32 v4, v4
	v_exp_f32_e32 v159, v159
	v_exp_f32_e32 v190, v190
	v_exp_f32_e32 v191, v191
	v_exp_f32_e32 v203, v203
	v_exp_f32_e32 v204, v204
	v_exp_f32_e32 v205, v205
	v_add_f32_e32 v3, 1.0, v3
	v_add_f32_e32 v4, 1.0, v4
	v_add_f32_e32 v159, 1.0, v159
	v_add_f32_e32 v190, 1.0, v190
	v_add_f32_e32 v191, 1.0, v191
	v_add_f32_e32 v203, 1.0, v203
	v_add_f32_e32 v204, 1.0, v204
	v_add_f32_e32 v205, 1.0, v205
	v_rcp_f32_e32 v3, v3
	v_rcp_f32_e32 v4, v4
	v_rcp_f32_e32 v159, v159
	v_rcp_f32_e32 v190, v190
	v_rcp_f32_e32 v191, v191
	v_rcp_f32_e32 v203, v203
	v_rcp_f32_e32 v204, v204
	v_rcp_f32_e32 v205, v205
	v_mul_f32_e32 v3, v18, v3
	v_mul_f32_e32 v4, v19, v4
	v_mul_f32_e32 v159, v20, v159
	v_mul_f32_e32 v190, v21, v190
	v_mul_f32_e32 v191, v14, v191
	v_mul_f32_e32 v203, v15, v203
	v_mul_f32_e32 v204, v16, v204
	v_mul_f32_e32 v205, v17, v205
	v_cvt_pk_bf16_f32 v240, v3, v4
	v_cvt_pk_bf16_f32 v241, v159, v190
	v_cvt_pk_bf16_f32 v242, v191, v203
	v_cvt_pk_bf16_f32 v243, v204, v205
	s_add_u32 s32, s44, 0xa0100
	s_addc_u32 s33, s45, 0
	global_store_dwordx4 v252, v[240:243], s[32:33]
	s_waitcnt vmcnt(15)
	v_lshlrev_b32_e32 v3, 16, v244
	v_and_b32_e32 v4, s74, v244
	v_lshlrev_b32_e32 v159, 16, v245
	v_and_b32_e32 v190, s74, v245
	v_lshlrev_b32_e32 v191, 16, v246
	v_and_b32_e32 v203, s74, v246
	v_lshlrev_b32_e32 v204, 16, v247
	v_and_b32_e32 v205, s74, v247
	v_max_f32_e32 v3, v3, v3
	v_max_f32_e32 v4, v4, v4
	v_max_f32_e32 v159, v159, v159
	v_max_f32_e32 v190, v190, v190
	v_max_f32_e32 v191, v191, v191
	v_max_f32_e32 v203, v203, v203
	v_max_f32_e32 v204, v204, v204
	v_max_f32_e32 v205, v205, v205
	v_max_f32_e32 v3, 0xc1f00000, v3
	v_max_f32_e32 v4, 0xc1f00000, v4
	v_max_f32_e32 v159, 0xc1f00000, v159
	v_max_f32_e32 v190, 0xc1f00000, v190
	v_max_f32_e32 v191, 0xc1f00000, v191
	v_max_f32_e32 v203, 0xc1f00000, v203
	v_max_f32_e32 v204, 0xc1f00000, v204
	v_max_f32_e32 v205, 0xc1f00000, v205
	v_mul_f32_e32 v3, 0xbfb8aa3b, v3
	v_mul_f32_e32 v4, 0xbfb8aa3b, v4
	v_mul_f32_e32 v159, 0xbfb8aa3b, v159
	v_mul_f32_e32 v190, 0xbfb8aa3b, v190
	v_mul_f32_e32 v191, 0xbfb8aa3b, v191
	v_mul_f32_e32 v203, 0xbfb8aa3b, v203
	v_mul_f32_e32 v204, 0xbfb8aa3b, v204
	v_mul_f32_e32 v205, 0xbfb8aa3b, v205
	v_exp_f32_e32 v3, v3
	v_exp_f32_e32 v4, v4
	v_exp_f32_e32 v159, v159
	v_exp_f32_e32 v190, v190
	v_exp_f32_e32 v191, v191
	v_exp_f32_e32 v203, v203
	v_exp_f32_e32 v204, v204
	v_exp_f32_e32 v205, v205
	v_add_f32_e32 v3, 1.0, v3
	v_add_f32_e32 v4, 1.0, v4
	v_add_f32_e32 v159, 1.0, v159
	v_add_f32_e32 v190, 1.0, v190
	v_add_f32_e32 v191, 1.0, v191
	v_add_f32_e32 v203, 1.0, v203
	v_add_f32_e32 v204, 1.0, v204
	v_add_f32_e32 v205, 1.0, v205
	v_rcp_f32_e32 v3, v3
	v_rcp_f32_e32 v4, v4
	v_rcp_f32_e32 v159, v159
	v_rcp_f32_e32 v190, v190
	v_rcp_f32_e32 v191, v191
	v_rcp_f32_e32 v203, v203
	v_rcp_f32_e32 v204, v204
	v_rcp_f32_e32 v205, v205
	v_mul_f32_e32 v3, v42, v3
	v_mul_f32_e32 v4, v43, v4
	v_mul_f32_e32 v159, v44, v159
	v_mul_f32_e32 v190, v45, v190
	v_mul_f32_e32 v191, v38, v191
	v_mul_f32_e32 v203, v39, v203
	v_mul_f32_e32 v204, v40, v204
	v_mul_f32_e32 v205, v41, v205
	v_cvt_pk_bf16_f32 v244, v3, v4
	v_cvt_pk_bf16_f32 v245, v159, v190
	v_cvt_pk_bf16_f32 v246, v191, v203
	v_cvt_pk_bf16_f32 v247, v204, v205
	s_add_u32 s32, s44, 0xb0000
	s_addc_u32 s33, s45, 0
	global_store_dwordx4 v252, v[244:247], s[32:33]
	s_waitcnt vmcnt(15)
	v_lshlrev_b32_e32 v3, 16, v248
	v_and_b32_e32 v4, s74, v248
	v_lshlrev_b32_e32 v159, 16, v249
	v_and_b32_e32 v190, s74, v249
	v_lshlrev_b32_e32 v191, 16, v250
	v_and_b32_e32 v203, s74, v250
	v_lshlrev_b32_e32 v204, 16, v251
	v_and_b32_e32 v205, s74, v251
	v_max_f32_e32 v3, v3, v3
	v_max_f32_e32 v4, v4, v4
	v_max_f32_e32 v159, v159, v159
	v_max_f32_e32 v190, v190, v190
	v_max_f32_e32 v191, v191, v191
	v_max_f32_e32 v203, v203, v203
	v_max_f32_e32 v204, v204, v204
	v_max_f32_e32 v205, v205, v205
	v_max_f32_e32 v3, 0xc1f00000, v3
	v_max_f32_e32 v4, 0xc1f00000, v4
	v_max_f32_e32 v159, 0xc1f00000, v159
	v_max_f32_e32 v190, 0xc1f00000, v190
	v_max_f32_e32 v191, 0xc1f00000, v191
	v_max_f32_e32 v203, 0xc1f00000, v203
	v_max_f32_e32 v204, 0xc1f00000, v204
	v_max_f32_e32 v205, 0xc1f00000, v205
	v_mul_f32_e32 v3, 0xbfb8aa3b, v3
	v_mul_f32_e32 v4, 0xbfb8aa3b, v4
	v_mul_f32_e32 v159, 0xbfb8aa3b, v159
	v_mul_f32_e32 v190, 0xbfb8aa3b, v190
	v_mul_f32_e32 v191, 0xbfb8aa3b, v191
	v_mul_f32_e32 v203, 0xbfb8aa3b, v203
	v_mul_f32_e32 v204, 0xbfb8aa3b, v204
	v_mul_f32_e32 v205, 0xbfb8aa3b, v205
	v_exp_f32_e32 v3, v3
	v_exp_f32_e32 v4, v4
	v_exp_f32_e32 v159, v159
	v_exp_f32_e32 v190, v190
	v_exp_f32_e32 v191, v191
	v_exp_f32_e32 v203, v203
	v_exp_f32_e32 v204, v204
	v_exp_f32_e32 v205, v205
	v_add_f32_e32 v3, 1.0, v3
	v_add_f32_e32 v4, 1.0, v4
	v_add_f32_e32 v159, 1.0, v159
	v_add_f32_e32 v190, 1.0, v190
	v_add_f32_e32 v191, 1.0, v191
	v_add_f32_e32 v203, 1.0, v203
	v_add_f32_e32 v204, 1.0, v204
	v_add_f32_e32 v205, 1.0, v205
	v_rcp_f32_e32 v3, v3
	v_rcp_f32_e32 v4, v4
	v_rcp_f32_e32 v159, v159
	v_rcp_f32_e32 v190, v190
	v_rcp_f32_e32 v191, v191
	v_rcp_f32_e32 v203, v203
	v_rcp_f32_e32 v204, v204
	v_rcp_f32_e32 v205, v205
	v_mul_f32_e32 v3, v10, v3
	v_mul_f32_e32 v4, v11, v4
	v_mul_f32_e32 v159, v12, v159
	v_mul_f32_e32 v190, v13, v190
	v_mul_f32_e32 v191, v6, v191
	v_mul_f32_e32 v203, v7, v203
	v_mul_f32_e32 v204, v8, v204
	v_mul_f32_e32 v205, v9, v205
	v_cvt_pk_bf16_f32 v248, v3, v4
	v_cvt_pk_bf16_f32 v249, v159, v190
	v_cvt_pk_bf16_f32 v250, v191, v203
	v_cvt_pk_bf16_f32 v251, v204, v205
	s_add_u32 s32, s44, 0xb0100
	s_addc_u32 s33, s45, 0
	global_store_dwordx4 v252, v[248:251], s[32:33]
.Lp4e_done:
	s_cmp_eq_u32 s1, 0
	s_cselect_b64 s[6:7], -1, 0
	v_or_b32_e32 v4, s75, v155
	v_mov_b32_e32 v5, 0
	s_andn2_b64 vcc, exec, s[4:5]
	s_mov_b64 s[4:5], -1
	s_cbranch_vccnz .LBB0_468
